# v96 plus M3 state-block loads in two batches and sample-row tails batched (F output part, J x/gate chunks, prologue sample row)
# speedup vs baseline: 1.0053x; 1.0053x over previous
.LBB0_96:
	s_abs_i32 s21, s53
	s_mul_hi_u32 s30, s21, s39
	s_mul_i32 s31, s30, s38
	s_ashr_i32 s20, s53, 31
	s_sub_i32 s21, s21, s31
	s_xor_b32 s20, s20, s43
	s_add_i32 s31, s30, 1
	s_sub_i32 s34, s21, s38
	s_cmp_ge_u32 s21, s38
	s_cselect_b32 s30, s31, s30
	s_cselect_b32 s21, s34, s21
	s_add_i32 s31, s30, 1
	s_cmp_ge_u32 s21, s38
	s_cselect_b32 s21, s31, s30
	s_xor_b32 s21, s21, s20
	s_sub_i32 s20, s21, s20
	s_add_i32 s20, s53, s20
	s_and_b32 s20, s20, 7
	v_readlane_b32 s21, v253, 15
	s_cmp_lg_u32 s21, s20
	s_cbranch_scc1 .LBB0_95
	s_lshr_b32 s21, s53, 3
	s_add_i32 s20, s53, 0x2000
	s_add_i32 s21, s21, 1
	s_cmp_gt_i32 s53, -1
	s_cselect_b32 s21, s21, 0
	s_mul_hi_u32 s30, s21, 0xc000
	s_mul_i32 s21, s21, 0xc000
	s_add_u32 s34, s24, s21
	s_addc_u32 s35, s25, s30
	s_waitcnt lgkmcnt(0)
	v_add_co_u32_e32 v2, vcc, 0xfffff000, v32
	v_lshl_add_u64 v[46:47], v[54:55], 2, s[34:35]
	s_nop 0
	v_addc_co_u32_e32 v3, vcc, -1, v33, vcc
	v_add_co_u32_e32 v42, vcc, s41, v46
	global_load_dwordx4 v[36:39], v[2:3], off offset:-3072
	global_load_dwordx4 v[120:123], v[2:3], off offset:-2048
	global_load_dwordx4 v[22:25], v[2:3], off offset:-1024
	global_load_dwordx4 v[18:21], v[32:33], off offset:-4096
	global_load_dwordx4 v[14:17], v[32:33], off offset:-3072
	global_load_dwordx4 v[10:13], v[32:33], off offset:-2048
	global_load_dwordx4 v[6:9], v[32:33], off offset:-1024
	s_nop 0
	global_load_dwordx4 v[2:5], v[32:33], off
	v_addc_co_u32_e32 v43, vcc, 0, v47, vcc
	global_load_dwordx4 v[124:127], v[42:43], off offset:-4096
	global_load_dwordx4 v[128:131], v[46:47], off
	s_ashr_i32 s21, s20, 31
	s_lshl_b64 s[30:31], s[20:21], 12
	v_lshl_add_u64 v[44:45], v[30:31], 0, s[30:31]
	v_lshl_add_u64 v[48:49], v[46:47], 0, s[26:27]
	s_waitcnt vmcnt(1)
	v_pk_add_f32 v[40:41], v[124:125], 1.0 op_sel_hi:[1,0]
	v_pk_add_f32 v[34:35], v[126:127], 1.0 op_sel_hi:[1,0]
	s_waitcnt vmcnt(0)
	v_pk_fma_f32 v[36:37], v[36:37], v[40:41], v[128:129]
	v_pk_fma_f32 v[34:35], v[38:39], v[34:35], v[130:131]
	v_cvt_pk_bf16_f32 v38, v36, v37
	v_cvt_pk_bf16_f32 v39, v34, v35
	global_store_dwordx2 v[44:45], v[38:39], off
	global_load_dwordx4 v[208:211], v[48:49], off offset:1024
	global_load_dwordx4 v[212:215], v[46:47], off offset:1024
	global_load_dwordx4 v[216:219], v[48:49], off offset:2048
	global_load_dwordx4 v[220:223], v[46:47], off offset:2048
	global_load_dwordx4 v[224:227], v[48:49], off offset:3072
	global_load_dwordx4 v[228:231], v[46:47], off offset:3072
	global_load_dwordx4 v[236:239], v[42:43], off
	s_waitcnt vmcnt(0)
	s_nop 1
	v_mov_b64_e32 v[38:39], v[208:209]
	v_mov_b64_e32 v[40:41], v[210:211]
	s_nop 0
	s_nop 1
	v_mov_b64_e32 v[124:125], v[212:213]
	v_mov_b64_e32 v[126:127], v[214:215]
	s_nop 0
	v_pk_add_f32 v[40:41], v[40:41], 1.0 op_sel_hi:[1,0]
	v_pk_add_f32 v[128:129], v[38:39], 1.0 op_sel_hi:[1,0]
	s_nop 0
	v_pk_fma_f32 v[38:39], v[122:123], v[40:41], v[126:127]
	v_pk_fma_f32 v[40:41], v[120:121], v[128:129], v[124:125]
	v_cvt_pk_bf16_f32 v120, v40, v41
	v_cvt_pk_bf16_f32 v121, v38, v39
	global_store_dwordx2 v[44:45], v[120:121], off offset:512
	s_nop 1
	v_mov_b64_e32 v[120:121], v[216:217]
	v_mov_b64_e32 v[122:123], v[218:219]
	s_nop 0
	s_nop 1
	v_mov_b64_e32 v[124:125], v[220:221]
	v_mov_b64_e32 v[126:127], v[222:223]
	s_nop 0
	v_pk_add_f32 v[120:121], v[120:121], 1.0 op_sel_hi:[1,0]
	s_nop 0
	v_pk_fma_f32 v[22:23], v[22:23], v[120:121], v[124:125]
	v_pk_add_f32 v[122:123], v[122:123], 1.0 op_sel_hi:[1,0]
	s_nop 0
	v_pk_fma_f32 v[24:25], v[24:25], v[122:123], v[126:127]
	v_cvt_pk_bf16_f32 v120, v22, v23
	v_cvt_pk_bf16_f32 v121, v24, v25
	global_store_dwordx2 v[44:45], v[120:121], off offset:1024
	s_nop 1
	v_mov_b64_e32 v[120:121], v[224:225]
	v_mov_b64_e32 v[122:123], v[226:227]
	s_nop 0
	s_nop 1
	v_mov_b64_e32 v[124:125], v[228:229]
	v_mov_b64_e32 v[126:127], v[230:231]
	s_nop 0
	v_pk_add_f32 v[120:121], v[120:121], 1.0 op_sel_hi:[1,0]
	v_pk_add_f32 v[48:49], v[122:123], 1.0 op_sel_hi:[1,0]
	s_nop 0
	v_pk_fma_f32 v[18:19], v[18:19], v[120:121], v[124:125]
	v_pk_fma_f32 v[20:21], v[20:21], v[48:49], v[126:127]
	v_cvt_pk_bf16_f32 v48, v18, v19
	v_cvt_pk_bf16_f32 v49, v20, v21
	global_store_dwordx2 v[44:45], v[48:49], off offset:1536
	v_add_co_u32_e32 v124, vcc, s48, v46
	s_nop 1
	v_mov_b64_e32 v[120:121], v[236:237]
	v_mov_b64_e32 v[122:123], v[238:239]
	s_nop 0
	v_addc_co_u32_e32 v125, vcc, 0, v47, vcc
	global_load_dwordx4 v[208:211], v[124:125], off
	global_load_dwordx4 v[212:215], v[42:43], off offset:1024
	global_load_dwordx4 v[216:219], v[124:125], off offset:1024
	global_load_dwordx4 v[220:223], v[42:43], off offset:2048
	global_load_dwordx4 v[224:227], v[124:125], off offset:2048
	global_load_dwordx4 v[228:231], v[42:43], off offset:3072
	global_load_dwordx4 v[236:239], v[124:125], off offset:3072
	s_waitcnt vmcnt(0)
	s_nop 1
	v_mov_b64_e32 v[46:47], v[208:209]
	v_mov_b64_e32 v[48:49], v[210:211]
	s_nop 0
	v_pk_add_f32 v[120:121], v[120:121], 1.0 op_sel_hi:[1,0]
	v_pk_add_f32 v[122:123], v[122:123], 1.0 op_sel_hi:[1,0]
	s_nop 0
	v_pk_fma_f32 v[14:15], v[14:15], v[120:121], v[46:47]
	s_nop 0
	v_pk_fma_f32 v[16:17], v[16:17], v[122:123], v[48:49]
	v_cvt_pk_bf16_f32 v46, v14, v15
	v_cvt_pk_bf16_f32 v47, v16, v17
	global_store_dwordx2 v[44:45], v[46:47], off offset:2048
	s_nop 1
	v_mov_b64_e32 v[46:47], v[212:213]
	v_mov_b64_e32 v[48:49], v[214:215]
	s_nop 0
	s_nop 1
	v_mov_b64_e32 v[120:121], v[216:217]
	v_mov_b64_e32 v[122:123], v[218:219]
	s_nop 0
	v_pk_add_f32 v[46:47], v[46:47], 1.0 op_sel_hi:[1,0]
	s_nop 0
	v_pk_fma_f32 v[10:11], v[10:11], v[46:47], v[120:121]
	v_pk_add_f32 v[48:49], v[48:49], 1.0 op_sel_hi:[1,0]
	s_nop 0
	v_pk_fma_f32 v[12:13], v[12:13], v[48:49], v[122:123]
	v_cvt_pk_bf16_f32 v46, v10, v11
	v_cvt_pk_bf16_f32 v47, v12, v13
	global_store_dwordx2 v[44:45], v[46:47], off offset:2560
	s_nop 1
	v_mov_b64_e32 v[46:47], v[220:221]
	v_mov_b64_e32 v[48:49], v[222:223]
	s_nop 0
	s_nop 1
	v_mov_b64_e32 v[120:121], v[224:225]
	v_mov_b64_e32 v[122:123], v[226:227]
	s_nop 0
	v_pk_add_f32 v[46:47], v[46:47], 1.0 op_sel_hi:[1,0]
	s_nop 0
	v_pk_fma_f32 v[6:7], v[6:7], v[46:47], v[120:121]
	v_pk_add_f32 v[48:49], v[48:49], 1.0 op_sel_hi:[1,0]
	s_nop 0
	v_pk_fma_f32 v[8:9], v[8:9], v[48:49], v[122:123]
	v_cvt_pk_bf16_f32 v46, v6, v7
	v_cvt_pk_bf16_f32 v47, v8, v9
	global_store_dwordx2 v[44:45], v[46:47], off offset:3072
	s_nop 1
	v_mov_b64_e32 v[46:47], v[228:229]
	v_mov_b64_e32 v[48:49], v[230:231]
	s_nop 0
	s_nop 1
	v_mov_b64_e32 v[120:121], v[236:237]
	v_mov_b64_e32 v[122:123], v[238:239]
	s_nop 0
	v_pk_add_f32 v[46:47], v[46:47], 1.0 op_sel_hi:[1,0]
	v_pk_add_f32 v[42:43], v[48:49], 1.0 op_sel_hi:[1,0]
	s_nop 0
	v_pk_fma_f32 v[2:3], v[2:3], v[46:47], v[120:121]
	v_pk_fma_f32 v[4:5], v[4:5], v[42:43], v[122:123]
	v_cvt_pk_bf16_f32 v42, v2, v3
	v_cvt_pk_bf16_f32 v43, v4, v5
	global_store_dwordx2 v[44:45], v[42:43], off offset:3584
	ds_read_b128 v[42:45], v50
	s_waitcnt lgkmcnt(0)
	v_pk_fma_f32 v[42:43], v[36:37], v[42:43], 0 op_sel_hi:[1,1,0]
	s_nop 0
	v_pk_fma_f32 v[46:47], v[34:35], v[44:45], v[42:43]
	ds_read_b128 v[42:45], v50 offset:1024
	s_waitcnt lgkmcnt(0)
	v_pk_fma_f32 v[42:43], v[40:41], v[42:43], v[46:47]
	s_nop 0
	v_pk_fma_f32 v[46:47], v[38:39], v[44:45], v[42:43]
	ds_read_b128 v[42:45], v50 offset:2048
	s_waitcnt lgkmcnt(0)
	v_pk_fma_f32 v[42:43], v[22:23], v[42:43], v[46:47]
	s_nop 0
	v_pk_fma_f32 v[46:47], v[24:25], v[44:45], v[42:43]
	ds_read_b128 v[42:45], v50 offset:3072
	s_waitcnt lgkmcnt(0)
	v_pk_fma_f32 v[42:43], v[18:19], v[42:43], v[46:47]
	s_nop 0
	v_pk_fma_f32 v[46:47], v[20:21], v[44:45], v[42:43]
	ds_read_b128 v[42:45], v50 offset:4096
	s_waitcnt lgkmcnt(0)
	v_pk_fma_f32 v[42:43], v[14:15], v[42:43], v[46:47]
	s_nop 0
	v_pk_fma_f32 v[46:47], v[16:17], v[44:45], v[42:43]
	ds_read_b128 v[42:45], v50 offset:5120
	s_waitcnt lgkmcnt(0)
	v_pk_fma_f32 v[42:43], v[10:11], v[42:43], v[46:47]
	s_nop 0
	v_pk_fma_f32 v[46:47], v[12:13], v[44:45], v[42:43]
	ds_read_b128 v[42:45], v50 offset:6144
	s_waitcnt lgkmcnt(0)
	v_pk_fma_f32 v[42:43], v[6:7], v[42:43], v[46:47]
	s_nop 0
	v_pk_fma_f32 v[46:47], v[8:9], v[44:45], v[42:43]
	ds_read_b128 v[42:45], v50 offset:7168
	s_waitcnt lgkmcnt(0)
	v_pk_fma_f32 v[42:43], v[2:3], v[42:43], v[46:47]
	s_nop 0
	v_pk_fma_f32 v[42:43], v[4:5], v[44:45], v[42:43]
	ds_read_b128 v[44:47], v50 offset:8192
	v_add_f32_e32 v42, v42, v43
	s_waitcnt lgkmcnt(0)
	v_pk_fma_f32 v[44:45], v[36:37], v[44:45], 0 op_sel_hi:[1,1,0]
	s_nop 0
	v_pk_fma_f32 v[48:49], v[34:35], v[46:47], v[44:45]
	ds_read_b128 v[44:47], v50 offset:9216
	s_waitcnt lgkmcnt(0)
	v_pk_fma_f32 v[44:45], v[40:41], v[44:45], v[48:49]
	s_nop 0
	v_pk_fma_f32 v[48:49], v[38:39], v[46:47], v[44:45]
	ds_read_b128 v[44:47], v50 offset:10240
	s_waitcnt lgkmcnt(0)
	v_pk_fma_f32 v[44:45], v[22:23], v[44:45], v[48:49]
	s_nop 0
	v_pk_fma_f32 v[48:49], v[24:25], v[46:47], v[44:45]
	ds_read_b128 v[44:47], v50 offset:11264
	s_waitcnt lgkmcnt(0)
	v_pk_fma_f32 v[44:45], v[18:19], v[44:45], v[48:49]
	s_nop 0
	v_pk_fma_f32 v[48:49], v[20:21], v[46:47], v[44:45]
	ds_read_b128 v[44:47], v50 offset:12288
	s_waitcnt lgkmcnt(0)
	v_pk_fma_f32 v[44:45], v[14:15], v[44:45], v[48:49]
	s_nop 0
	v_pk_fma_f32 v[48:49], v[16:17], v[46:47], v[44:45]
	ds_read_b128 v[44:47], v50 offset:13312
	s_waitcnt lgkmcnt(0)
	v_pk_fma_f32 v[44:45], v[10:11], v[44:45], v[48:49]
	s_nop 0
	v_pk_fma_f32 v[48:49], v[12:13], v[46:47], v[44:45]
	ds_read_b128 v[44:47], v50 offset:14336
	s_waitcnt lgkmcnt(0)
	v_pk_fma_f32 v[44:45], v[6:7], v[44:45], v[48:49]
	s_nop 0
	v_pk_fma_f32 v[48:49], v[8:9], v[46:47], v[44:45]
	ds_read_b128 v[44:47], v50 offset:15360
	s_waitcnt lgkmcnt(0)
	v_pk_fma_f32 v[44:45], v[2:3], v[44:45], v[48:49]
	s_nop 0
	v_pk_fma_f32 v[44:45], v[4:5], v[46:47], v[44:45]
	s_nop 0
	v_add_f32_e32 v43, v44, v45
	ds_read_b128 v[44:47], v50 offset:16384
	s_waitcnt lgkmcnt(0)
	v_pk_fma_f32 v[44:45], v[36:37], v[44:45], 0 op_sel_hi:[1,1,0]
	s_nop 0
	v_pk_fma_f32 v[48:49], v[34:35], v[46:47], v[44:45]
	ds_read_b128 v[44:47], v50 offset:17408
	s_waitcnt lgkmcnt(0)
	v_pk_fma_f32 v[44:45], v[40:41], v[44:45], v[48:49]
	s_nop 0
	v_pk_fma_f32 v[48:49], v[38:39], v[46:47], v[44:45]
	ds_read_b128 v[44:47], v50 offset:18432
	s_waitcnt lgkmcnt(0)
	v_pk_fma_f32 v[44:45], v[22:23], v[44:45], v[48:49]
	s_nop 0
	v_pk_fma_f32 v[48:49], v[24:25], v[46:47], v[44:45]
	ds_read_b128 v[44:47], v50 offset:19456
	s_waitcnt lgkmcnt(0)
	v_pk_fma_f32 v[44:45], v[18:19], v[44:45], v[48:49]
	s_nop 0
	v_pk_fma_f32 v[48:49], v[20:21], v[46:47], v[44:45]
	ds_read_b128 v[44:47], v50 offset:20480
	s_waitcnt lgkmcnt(0)
	v_pk_fma_f32 v[44:45], v[14:15], v[44:45], v[48:49]
	s_nop 0
	v_pk_fma_f32 v[48:49], v[16:17], v[46:47], v[44:45]
	ds_read_b128 v[44:47], v50 offset:21504
	s_waitcnt lgkmcnt(0)
	v_pk_fma_f32 v[44:45], v[10:11], v[44:45], v[48:49]
	s_nop 0
	v_pk_fma_f32 v[48:49], v[12:13], v[46:47], v[44:45]
	ds_read_b128 v[44:47], v50 offset:22528
	s_waitcnt lgkmcnt(0)
	v_pk_fma_f32 v[44:45], v[6:7], v[44:45], v[48:49]
	s_nop 0
	v_pk_fma_f32 v[48:49], v[8:9], v[46:47], v[44:45]
	ds_read_b128 v[44:47], v50 offset:23552
	s_waitcnt lgkmcnt(0)
	v_pk_fma_f32 v[44:45], v[2:3], v[44:45], v[48:49]
	s_nop 0
	v_pk_fma_f32 v[44:45], v[4:5], v[46:47], v[44:45]
	ds_read_b128 v[46:49], v50 offset:24576
	v_add_f32_e32 v44, v44, v45
	s_waitcnt lgkmcnt(0)
	v_pk_fma_f32 v[46:47], v[36:37], v[46:47], 0 op_sel_hi:[1,1,0]
	s_nop 0
	v_pk_fma_f32 v[120:121], v[34:35], v[48:49], v[46:47]
	ds_read_b128 v[46:49], v50 offset:25600
	s_waitcnt lgkmcnt(0)
	v_pk_fma_f32 v[46:47], v[40:41], v[46:47], v[120:121]
	s_nop 0
	v_pk_fma_f32 v[120:121], v[38:39], v[48:49], v[46:47]
	ds_read_b128 v[46:49], v50 offset:26624
	s_waitcnt lgkmcnt(0)
	v_pk_fma_f32 v[46:47], v[22:23], v[46:47], v[120:121]
	s_nop 0
	v_pk_fma_f32 v[120:121], v[24:25], v[48:49], v[46:47]
	ds_read_b128 v[46:49], v50 offset:27648
	s_waitcnt lgkmcnt(0)
	v_pk_fma_f32 v[46:47], v[18:19], v[46:47], v[120:121]
	s_nop 0
	v_pk_fma_f32 v[120:121], v[20:21], v[48:49], v[46:47]
	ds_read_b128 v[46:49], v50 offset:28672
	s_waitcnt lgkmcnt(0)
	v_pk_fma_f32 v[46:47], v[14:15], v[46:47], v[120:121]
	s_nop 0
	v_pk_fma_f32 v[120:121], v[16:17], v[48:49], v[46:47]
	ds_read_b128 v[46:49], v50 offset:29696
	s_waitcnt lgkmcnt(0)
	v_pk_fma_f32 v[46:47], v[10:11], v[46:47], v[120:121]
	s_nop 0
	v_pk_fma_f32 v[120:121], v[12:13], v[48:49], v[46:47]
	ds_read_b128 v[46:49], v50 offset:30720
	s_waitcnt lgkmcnt(0)
	v_pk_fma_f32 v[46:47], v[6:7], v[46:47], v[120:121]
	s_nop 0
	v_pk_fma_f32 v[120:121], v[8:9], v[48:49], v[46:47]
	ds_read_b128 v[46:49], v50 offset:31744
	s_waitcnt lgkmcnt(0)
	v_pk_fma_f32 v[46:47], v[2:3], v[46:47], v[120:121]
	s_nop 0
	v_pk_fma_f32 v[46:47], v[4:5], v[48:49], v[46:47]
	s_nop 0
	v_add_f32_e32 v45, v46, v47
	ds_read_b128 v[46:49], v50 offset:32768
	s_waitcnt lgkmcnt(0)
	v_pk_fma_f32 v[46:47], v[36:37], v[46:47], 0 op_sel_hi:[1,1,0]
	s_nop 0
	v_pk_fma_f32 v[120:121], v[34:35], v[48:49], v[46:47]
	ds_read_b128 v[46:49], v50 offset:33792
	s_waitcnt lgkmcnt(0)
	v_pk_fma_f32 v[46:47], v[40:41], v[46:47], v[120:121]
	s_nop 0
	v_pk_fma_f32 v[120:121], v[38:39], v[48:49], v[46:47]
	ds_read_b128 v[46:49], v50 offset:34816
	s_waitcnt lgkmcnt(0)
	v_pk_fma_f32 v[46:47], v[22:23], v[46:47], v[120:121]
	s_nop 0
	v_pk_fma_f32 v[120:121], v[24:25], v[48:49], v[46:47]
	ds_read_b128 v[46:49], v50 offset:35840
	s_waitcnt lgkmcnt(0)
	v_pk_fma_f32 v[46:47], v[18:19], v[46:47], v[120:121]
	s_nop 0
	v_pk_fma_f32 v[120:121], v[20:21], v[48:49], v[46:47]
	ds_read_b128 v[46:49], v50 offset:36864
	s_waitcnt lgkmcnt(0)
	v_pk_fma_f32 v[46:47], v[14:15], v[46:47], v[120:121]
	s_nop 0
	v_pk_fma_f32 v[120:121], v[16:17], v[48:49], v[46:47]
	ds_read_b128 v[46:49], v50 offset:37888
	s_waitcnt lgkmcnt(0)
	v_pk_fma_f32 v[46:47], v[10:11], v[46:47], v[120:121]
	s_nop 0
	v_pk_fma_f32 v[120:121], v[12:13], v[48:49], v[46:47]
	ds_read_b128 v[46:49], v50 offset:38912
	s_waitcnt lgkmcnt(0)
	v_pk_fma_f32 v[46:47], v[6:7], v[46:47], v[120:121]
	s_nop 0
	v_pk_fma_f32 v[120:121], v[8:9], v[48:49], v[46:47]
	ds_read_b128 v[46:49], v50 offset:39936
	s_waitcnt lgkmcnt(0)
	v_pk_fma_f32 v[46:47], v[2:3], v[46:47], v[120:121]
	ds_read_b128 v[120:123], v50 offset:40960
	v_pk_fma_f32 v[46:47], v[4:5], v[48:49], v[46:47]
	s_waitcnt lgkmcnt(0)
	v_pk_fma_f32 v[48:49], v[36:37], v[120:121], 0 op_sel_hi:[1,1,0]
	s_nop 0
	v_pk_fma_f32 v[48:49], v[34:35], v[122:123], v[48:49]
	ds_read_b128 v[120:123], v50 offset:41984
	v_add_f32_e32 v46, v46, v47
	s_waitcnt lgkmcnt(0)
	v_pk_fma_f32 v[48:49], v[40:41], v[120:121], v[48:49]
	s_nop 0
	v_pk_fma_f32 v[48:49], v[38:39], v[122:123], v[48:49]
	ds_read_b128 v[120:123], v50 offset:43008
	s_waitcnt lgkmcnt(0)
	v_pk_fma_f32 v[48:49], v[22:23], v[120:121], v[48:49]
	s_nop 0
	v_pk_fma_f32 v[48:49], v[24:25], v[122:123], v[48:49]
	ds_read_b128 v[120:123], v50 offset:44032
	s_waitcnt lgkmcnt(0)
	v_pk_fma_f32 v[48:49], v[18:19], v[120:121], v[48:49]
	s_nop 0
	v_pk_fma_f32 v[48:49], v[20:21], v[122:123], v[48:49]
	ds_read_b128 v[120:123], v50 offset:45056
	s_waitcnt lgkmcnt(0)
	v_pk_fma_f32 v[48:49], v[14:15], v[120:121], v[48:49]
	s_nop 0
	v_pk_fma_f32 v[48:49], v[16:17], v[122:123], v[48:49]
	ds_read_b128 v[120:123], v50 offset:46080
	s_waitcnt lgkmcnt(0)
	v_pk_fma_f32 v[48:49], v[10:11], v[120:121], v[48:49]
	s_nop 0
	v_pk_fma_f32 v[48:49], v[12:13], v[122:123], v[48:49]
	ds_read_b128 v[120:123], v50 offset:47104
	s_waitcnt lgkmcnt(0)
	v_pk_fma_f32 v[48:49], v[6:7], v[120:121], v[48:49]
	s_nop 0
	v_pk_fma_f32 v[48:49], v[8:9], v[122:123], v[48:49]
	ds_read_b128 v[120:123], v50 offset:48128
	s_waitcnt lgkmcnt(0)
	v_pk_fma_f32 v[48:49], v[2:3], v[120:121], v[48:49]
	s_nop 0
	v_pk_fma_f32 v[48:49], v[4:5], v[122:123], v[48:49]
	ds_read_b128 v[120:123], v50 offset:49152
	v_add_f32_e32 v47, v48, v49
	s_waitcnt lgkmcnt(0)
	v_pk_fma_f32 v[48:49], v[36:37], v[120:121], 0 op_sel_hi:[1,1,0]
	s_nop 0
	v_pk_fma_f32 v[48:49], v[34:35], v[122:123], v[48:49]
	ds_read_b128 v[120:123], v50 offset:50176
	s_waitcnt lgkmcnt(0)
	v_pk_fma_f32 v[48:49], v[40:41], v[120:121], v[48:49]
	s_nop 0
	v_pk_fma_f32 v[48:49], v[38:39], v[122:123], v[48:49]
	ds_read_b128 v[120:123], v50 offset:51200
	s_waitcnt lgkmcnt(0)
	v_pk_fma_f32 v[48:49], v[22:23], v[120:121], v[48:49]
	s_nop 0
	v_pk_fma_f32 v[48:49], v[24:25], v[122:123], v[48:49]
	ds_read_b128 v[120:123], v50 offset:52224
	s_waitcnt lgkmcnt(0)
	v_pk_fma_f32 v[48:49], v[18:19], v[120:121], v[48:49]
	s_nop 0
	v_pk_fma_f32 v[48:49], v[20:21], v[122:123], v[48:49]
	ds_read_b128 v[120:123], v50 offset:53248
	s_waitcnt lgkmcnt(0)
	v_pk_fma_f32 v[48:49], v[14:15], v[120:121], v[48:49]
	s_nop 0
	v_pk_fma_f32 v[48:49], v[16:17], v[122:123], v[48:49]
	ds_read_b128 v[120:123], v50 offset:54272
	s_waitcnt lgkmcnt(0)
	v_pk_fma_f32 v[48:49], v[10:11], v[120:121], v[48:49]
	s_nop 0
	v_pk_fma_f32 v[48:49], v[12:13], v[122:123], v[48:49]
	ds_read_b128 v[120:123], v50 offset:55296
	s_waitcnt lgkmcnt(0)
	v_pk_fma_f32 v[48:49], v[6:7], v[120:121], v[48:49]
	s_nop 0
	v_pk_fma_f32 v[48:49], v[8:9], v[122:123], v[48:49]
	ds_read_b128 v[120:123], v50 offset:56320
	s_waitcnt lgkmcnt(0)
	v_pk_fma_f32 v[48:49], v[2:3], v[120:121], v[48:49]
	s_nop 0
	v_pk_fma_f32 v[48:49], v[4:5], v[122:123], v[48:49]
	ds_read_b128 v[120:123], v50 offset:57344
	v_add_f32_e32 v48, v48, v49
	s_waitcnt lgkmcnt(0)
	v_pk_fma_f32 v[120:121], v[36:37], v[120:121], 0 op_sel_hi:[1,1,0]
	s_nop 0
	v_pk_fma_f32 v[124:125], v[34:35], v[122:123], v[120:121]
	ds_read_b128 v[120:123], v50 offset:58368
	s_waitcnt lgkmcnt(0)
	v_pk_fma_f32 v[120:121], v[40:41], v[120:121], v[124:125]
	s_nop 0
	v_pk_fma_f32 v[124:125], v[38:39], v[122:123], v[120:121]
	ds_read_b128 v[120:123], v50 offset:59392
	s_waitcnt lgkmcnt(0)
	v_pk_fma_f32 v[120:121], v[22:23], v[120:121], v[124:125]
	s_nop 0
	v_pk_fma_f32 v[124:125], v[24:25], v[122:123], v[120:121]
	ds_read_b128 v[120:123], v50 offset:60416
	s_waitcnt lgkmcnt(0)
	v_pk_fma_f32 v[120:121], v[18:19], v[120:121], v[124:125]
	s_nop 0
	v_pk_fma_f32 v[124:125], v[20:21], v[122:123], v[120:121]
	ds_read_b128 v[120:123], v50 offset:61440
	s_waitcnt lgkmcnt(0)
	v_pk_fma_f32 v[120:121], v[14:15], v[120:121], v[124:125]
	s_nop 0
	v_pk_fma_f32 v[124:125], v[16:17], v[122:123], v[120:121]
	ds_read_b128 v[120:123], v50 offset:62464
	s_waitcnt lgkmcnt(0)
	v_pk_fma_f32 v[120:121], v[10:11], v[120:121], v[124:125]
	s_nop 0
	v_pk_fma_f32 v[124:125], v[12:13], v[122:123], v[120:121]
	ds_read_b128 v[120:123], v50 offset:63488
	s_waitcnt lgkmcnt(0)
	v_pk_fma_f32 v[120:121], v[6:7], v[120:121], v[124:125]
	s_nop 0
	v_pk_fma_f32 v[124:125], v[8:9], v[122:123], v[120:121]
	ds_read_b128 v[120:123], v50 offset:64512
	s_waitcnt lgkmcnt(0)
	v_pk_fma_f32 v[120:121], v[2:3], v[120:121], v[124:125]
	s_nop 0
	v_pk_fma_f32 v[120:121], v[4:5], v[122:123], v[120:121]
	s_nop 0
	v_add_f32_e32 v49, v120, v121
	ds_read_b128 v[120:123], v51
	s_waitcnt lgkmcnt(0)
	v_pk_fma_f32 v[120:121], v[36:37], v[120:121], 0 op_sel_hi:[1,1,0]
	s_nop 0
	v_pk_fma_f32 v[124:125], v[34:35], v[122:123], v[120:121]
	ds_read_b128 v[120:123], v52
	s_waitcnt lgkmcnt(0)
	v_pk_fma_f32 v[120:121], v[40:41], v[120:121], v[124:125]
	s_nop 0
	v_pk_fma_f32 v[124:125], v[38:39], v[122:123], v[120:121]
	ds_read_b128 v[120:123], v53
	s_waitcnt lgkmcnt(0)
	v_pk_fma_f32 v[120:121], v[22:23], v[120:121], v[124:125]
	s_nop 0
	v_pk_fma_f32 v[124:125], v[24:25], v[122:123], v[120:121]
	ds_read_b128 v[120:123], v56
	s_waitcnt lgkmcnt(0)
	v_pk_fma_f32 v[120:121], v[18:19], v[120:121], v[124:125]
	s_nop 0
	v_pk_fma_f32 v[124:125], v[20:21], v[122:123], v[120:121]
	ds_read_b128 v[120:123], v57
	s_waitcnt lgkmcnt(0)
	v_pk_fma_f32 v[120:121], v[14:15], v[120:121], v[124:125]
	s_nop 0
	v_pk_fma_f32 v[124:125], v[16:17], v[122:123], v[120:121]
	ds_read_b128 v[120:123], v58
	s_waitcnt lgkmcnt(0)
	v_pk_fma_f32 v[120:121], v[10:11], v[120:121], v[124:125]
	s_nop 0
	v_pk_fma_f32 v[124:125], v[12:13], v[122:123], v[120:121]
	ds_read_b128 v[120:123], v59
	s_waitcnt lgkmcnt(0)
	v_pk_fma_f32 v[120:121], v[6:7], v[120:121], v[124:125]
	s_nop 0
	v_pk_fma_f32 v[124:125], v[8:9], v[122:123], v[120:121]
	ds_read_b128 v[120:123], v60
	s_waitcnt lgkmcnt(0)
	v_pk_fma_f32 v[120:121], v[2:3], v[120:121], v[124:125]
	s_nop 0
	v_pk_fma_f32 v[120:121], v[4:5], v[122:123], v[120:121]
	ds_read_b128 v[122:125], v61
	v_add_f32_e32 v120, v120, v121
	s_waitcnt lgkmcnt(0)
	v_pk_fma_f32 v[122:123], v[36:37], v[122:123], 0 op_sel_hi:[1,1,0]
	s_nop 0
	v_pk_fma_f32 v[126:127], v[34:35], v[124:125], v[122:123]
	ds_read_b128 v[122:125], v62
	s_waitcnt lgkmcnt(0)
	v_pk_fma_f32 v[122:123], v[40:41], v[122:123], v[126:127]
	s_nop 0
	v_pk_fma_f32 v[126:127], v[38:39], v[124:125], v[122:123]
	ds_read_b128 v[122:125], v63
	s_waitcnt lgkmcnt(0)
	v_pk_fma_f32 v[122:123], v[22:23], v[122:123], v[126:127]
	s_nop 0
	v_pk_fma_f32 v[126:127], v[24:25], v[124:125], v[122:123]
	ds_read_b128 v[122:125], v64
	s_waitcnt lgkmcnt(0)
	v_pk_fma_f32 v[122:123], v[18:19], v[122:123], v[126:127]
	s_nop 0
	v_pk_fma_f32 v[126:127], v[20:21], v[124:125], v[122:123]
	ds_read_b128 v[122:125], v65
	s_waitcnt lgkmcnt(0)
	v_pk_fma_f32 v[122:123], v[14:15], v[122:123], v[126:127]
	s_nop 0
	v_pk_fma_f32 v[126:127], v[16:17], v[124:125], v[122:123]
	ds_read_b128 v[122:125], v66
	s_waitcnt lgkmcnt(0)
	v_pk_fma_f32 v[122:123], v[10:11], v[122:123], v[126:127]
	s_nop 0
	v_pk_fma_f32 v[126:127], v[12:13], v[124:125], v[122:123]
	ds_read_b128 v[122:125], v67
	s_waitcnt lgkmcnt(0)
	v_pk_fma_f32 v[122:123], v[6:7], v[122:123], v[126:127]
	s_nop 0
	v_pk_fma_f32 v[126:127], v[8:9], v[124:125], v[122:123]
	ds_read_b128 v[122:125], v68
	s_waitcnt lgkmcnt(0)
	v_pk_fma_f32 v[122:123], v[2:3], v[122:123], v[126:127]
	s_nop 0
	v_pk_fma_f32 v[122:123], v[4:5], v[124:125], v[122:123]
	s_nop 0
	v_add_f32_e32 v121, v122, v123
	ds_read_b128 v[122:125], v69
	s_waitcnt lgkmcnt(0)
	v_pk_fma_f32 v[122:123], v[36:37], v[122:123], 0 op_sel_hi:[1,1,0]
	s_nop 0
	v_pk_fma_f32 v[126:127], v[34:35], v[124:125], v[122:123]
	ds_read_b128 v[122:125], v70
	s_waitcnt lgkmcnt(0)
	v_pk_fma_f32 v[122:123], v[40:41], v[122:123], v[126:127]
	s_nop 0
	v_pk_fma_f32 v[126:127], v[38:39], v[124:125], v[122:123]
	ds_read_b128 v[122:125], v71
	s_waitcnt lgkmcnt(0)
	v_pk_fma_f32 v[122:123], v[22:23], v[122:123], v[126:127]
	s_nop 0
	v_pk_fma_f32 v[126:127], v[24:25], v[124:125], v[122:123]
	ds_read_b128 v[122:125], v72
	s_waitcnt lgkmcnt(0)
	v_pk_fma_f32 v[122:123], v[18:19], v[122:123], v[126:127]
	s_nop 0
	v_pk_fma_f32 v[126:127], v[20:21], v[124:125], v[122:123]
	ds_read_b128 v[122:125], v73
	s_waitcnt lgkmcnt(0)
	v_pk_fma_f32 v[122:123], v[14:15], v[122:123], v[126:127]
	s_nop 0
	v_pk_fma_f32 v[126:127], v[16:17], v[124:125], v[122:123]
	ds_read_b128 v[122:125], v74
	s_waitcnt lgkmcnt(0)
	v_pk_fma_f32 v[122:123], v[10:11], v[122:123], v[126:127]
	s_nop 0
	v_pk_fma_f32 v[126:127], v[12:13], v[124:125], v[122:123]
	ds_read_b128 v[122:125], v75
	s_waitcnt lgkmcnt(0)
	v_pk_fma_f32 v[122:123], v[6:7], v[122:123], v[126:127]
	s_nop 0
	v_pk_fma_f32 v[126:127], v[8:9], v[124:125], v[122:123]
	ds_read_b128 v[122:125], v76
	s_waitcnt lgkmcnt(0)
	v_pk_fma_f32 v[122:123], v[2:3], v[122:123], v[126:127]
	s_nop 0
	v_pk_fma_f32 v[122:123], v[4:5], v[124:125], v[122:123]
	ds_read_b128 v[124:127], v77
	v_add_f32_e32 v122, v122, v123
	s_waitcnt lgkmcnt(0)
	v_pk_fma_f32 v[124:125], v[36:37], v[124:125], 0 op_sel_hi:[1,1,0]
	s_nop 0
	v_pk_fma_f32 v[128:129], v[34:35], v[126:127], v[124:125]
	ds_read_b128 v[124:127], v78
	s_waitcnt lgkmcnt(0)
	v_pk_fma_f32 v[124:125], v[40:41], v[124:125], v[128:129]
	s_nop 0
	v_pk_fma_f32 v[128:129], v[38:39], v[126:127], v[124:125]
	ds_read_b128 v[124:127], v79
	s_waitcnt lgkmcnt(0)
	v_pk_fma_f32 v[124:125], v[22:23], v[124:125], v[128:129]
	s_nop 0
	v_pk_fma_f32 v[128:129], v[24:25], v[126:127], v[124:125]
	ds_read_b128 v[124:127], v80
	s_waitcnt lgkmcnt(0)
	v_pk_fma_f32 v[124:125], v[18:19], v[124:125], v[128:129]
	s_nop 0
	v_pk_fma_f32 v[128:129], v[20:21], v[126:127], v[124:125]
	ds_read_b128 v[124:127], v81
	s_waitcnt lgkmcnt(0)
	v_pk_fma_f32 v[124:125], v[14:15], v[124:125], v[128:129]
	s_nop 0
	v_pk_fma_f32 v[128:129], v[16:17], v[126:127], v[124:125]
	ds_read_b128 v[124:127], v82
	s_waitcnt lgkmcnt(0)
	v_pk_fma_f32 v[124:125], v[10:11], v[124:125], v[128:129]
	s_nop 0
	v_pk_fma_f32 v[128:129], v[12:13], v[126:127], v[124:125]
	ds_read_b128 v[124:127], v83
	s_waitcnt lgkmcnt(0)
	v_pk_fma_f32 v[124:125], v[6:7], v[124:125], v[128:129]
	s_nop 0
	v_pk_fma_f32 v[128:129], v[8:9], v[126:127], v[124:125]
	ds_read_b128 v[124:127], v85
	s_waitcnt lgkmcnt(0)
	v_pk_fma_f32 v[124:125], v[2:3], v[124:125], v[128:129]
	s_nop 0
	v_pk_fma_f32 v[124:125], v[4:5], v[126:127], v[124:125]
	s_nop 0
	v_add_f32_e32 v123, v124, v125
	ds_read_b128 v[124:127], v86
	s_waitcnt lgkmcnt(0)
	v_pk_fma_f32 v[124:125], v[36:37], v[124:125], 0 op_sel_hi:[1,1,0]
	s_nop 0
	v_pk_fma_f32 v[128:129], v[34:35], v[126:127], v[124:125]
	ds_read_b128 v[124:127], v87
	s_waitcnt lgkmcnt(0)
	v_pk_fma_f32 v[124:125], v[40:41], v[124:125], v[128:129]
	s_nop 0
	v_pk_fma_f32 v[128:129], v[38:39], v[126:127], v[124:125]
	ds_read_b128 v[124:127], v88
	s_waitcnt lgkmcnt(0)
	v_pk_fma_f32 v[124:125], v[22:23], v[124:125], v[128:129]
	s_nop 0
	v_pk_fma_f32 v[128:129], v[24:25], v[126:127], v[124:125]
	ds_read_b128 v[124:127], v89
	s_waitcnt lgkmcnt(0)
	v_pk_fma_f32 v[124:125], v[18:19], v[124:125], v[128:129]
	s_nop 0
	v_pk_fma_f32 v[128:129], v[20:21], v[126:127], v[124:125]
	ds_read_b128 v[124:127], v90
	s_waitcnt lgkmcnt(0)
	v_pk_fma_f32 v[124:125], v[14:15], v[124:125], v[128:129]
	s_nop 0
	v_pk_fma_f32 v[128:129], v[16:17], v[126:127], v[124:125]
	ds_read_b128 v[124:127], v91
	s_waitcnt lgkmcnt(0)
	v_pk_fma_f32 v[124:125], v[10:11], v[124:125], v[128:129]
	s_nop 0
	v_pk_fma_f32 v[128:129], v[12:13], v[126:127], v[124:125]
	ds_read_b128 v[124:127], v92
	s_waitcnt lgkmcnt(0)
	v_pk_fma_f32 v[124:125], v[6:7], v[124:125], v[128:129]
	s_nop 0
	v_pk_fma_f32 v[128:129], v[8:9], v[126:127], v[124:125]
	ds_read_b128 v[124:127], v93
	s_waitcnt lgkmcnt(0)
	v_pk_fma_f32 v[124:125], v[2:3], v[124:125], v[128:129]
	s_nop 0
	v_pk_fma_f32 v[124:125], v[4:5], v[126:127], v[124:125]
	ds_read_b128 v[126:129], v94
	v_add_f32_e32 v124, v124, v125
	s_waitcnt lgkmcnt(0)
	v_pk_fma_f32 v[126:127], v[36:37], v[126:127], 0 op_sel_hi:[1,1,0]
	s_nop 0
	v_pk_fma_f32 v[130:131], v[34:35], v[128:129], v[126:127]
	ds_read_b128 v[126:129], v95
	s_waitcnt lgkmcnt(0)
	v_pk_fma_f32 v[126:127], v[40:41], v[126:127], v[130:131]
	s_nop 0
	v_pk_fma_f32 v[130:131], v[38:39], v[128:129], v[126:127]
	ds_read_b128 v[126:129], v96
	s_waitcnt lgkmcnt(0)
	v_pk_fma_f32 v[126:127], v[22:23], v[126:127], v[130:131]
	s_nop 0
	v_pk_fma_f32 v[130:131], v[24:25], v[128:129], v[126:127]
	ds_read_b128 v[126:129], v97
	s_waitcnt lgkmcnt(0)
	v_pk_fma_f32 v[126:127], v[18:19], v[126:127], v[130:131]
	s_nop 0
	v_pk_fma_f32 v[130:131], v[20:21], v[128:129], v[126:127]
	ds_read_b128 v[126:129], v98
	s_waitcnt lgkmcnt(0)
	v_pk_fma_f32 v[126:127], v[14:15], v[126:127], v[130:131]
	s_nop 0
	v_pk_fma_f32 v[130:131], v[16:17], v[128:129], v[126:127]
	ds_read_b128 v[126:129], v99
	s_waitcnt lgkmcnt(0)
	v_pk_fma_f32 v[126:127], v[10:11], v[126:127], v[130:131]
	s_nop 0
	v_pk_fma_f32 v[130:131], v[12:13], v[128:129], v[126:127]
	ds_read_b128 v[126:129], v100
	s_waitcnt lgkmcnt(0)
	v_pk_fma_f32 v[126:127], v[6:7], v[126:127], v[130:131]
	s_nop 0
	v_pk_fma_f32 v[130:131], v[8:9], v[128:129], v[126:127]
	ds_read_b128 v[126:129], v101
	s_waitcnt lgkmcnt(0)
	v_pk_fma_f32 v[126:127], v[2:3], v[126:127], v[130:131]
	s_nop 0
	v_pk_fma_f32 v[126:127], v[4:5], v[128:129], v[126:127]
	s_nop 0
	v_add_f32_e32 v125, v126, v127
	ds_read_b128 v[126:129], v102
	s_waitcnt lgkmcnt(0)
	v_pk_fma_f32 v[126:127], v[36:37], v[126:127], 0 op_sel_hi:[1,1,0]
	s_nop 0
	v_pk_fma_f32 v[130:131], v[34:35], v[128:129], v[126:127]
	ds_read_b128 v[126:129], v103
	s_waitcnt lgkmcnt(0)
	v_pk_fma_f32 v[126:127], v[40:41], v[126:127], v[130:131]
	s_nop 0
	v_pk_fma_f32 v[130:131], v[38:39], v[128:129], v[126:127]
	ds_read_b128 v[126:129], v104
	s_waitcnt lgkmcnt(0)
	v_pk_fma_f32 v[126:127], v[22:23], v[126:127], v[130:131]
	s_nop 0
	v_pk_fma_f32 v[130:131], v[24:25], v[128:129], v[126:127]
	ds_read_b128 v[126:129], v105
	s_waitcnt lgkmcnt(0)
	v_pk_fma_f32 v[126:127], v[18:19], v[126:127], v[130:131]
	s_nop 0
	v_pk_fma_f32 v[130:131], v[20:21], v[128:129], v[126:127]
	ds_read_b128 v[126:129], v106
	s_waitcnt lgkmcnt(0)
	v_pk_fma_f32 v[126:127], v[14:15], v[126:127], v[130:131]
	s_nop 0
	v_pk_fma_f32 v[130:131], v[16:17], v[128:129], v[126:127]
	ds_read_b128 v[126:129], v107
	s_waitcnt lgkmcnt(0)
	v_pk_fma_f32 v[126:127], v[10:11], v[126:127], v[130:131]
	s_nop 0
	v_pk_fma_f32 v[130:131], v[12:13], v[128:129], v[126:127]
	ds_read_b128 v[126:129], v108
	s_waitcnt lgkmcnt(0)
	v_pk_fma_f32 v[126:127], v[6:7], v[126:127], v[130:131]
	s_nop 0
	v_pk_fma_f32 v[130:131], v[8:9], v[128:129], v[126:127]
	ds_read_b128 v[126:129], v109
	s_waitcnt lgkmcnt(0)
	v_pk_fma_f32 v[126:127], v[2:3], v[126:127], v[130:131]
	s_nop 0
	v_pk_fma_f32 v[126:127], v[4:5], v[128:129], v[126:127]
	ds_read_b128 v[128:131], v110
	v_add_f32_e32 v126, v126, v127
	s_waitcnt lgkmcnt(0)
	v_pk_fma_f32 v[36:37], v[36:37], v[128:129], 0 op_sel_hi:[1,1,0]
	s_nop 0
	v_pk_fma_f32 v[128:129], v[34:35], v[130:131], v[36:37]
	ds_read_b128 v[34:37], v111
	s_waitcnt lgkmcnt(0)
	v_pk_fma_f32 v[34:35], v[40:41], v[34:35], v[128:129]
	s_nop 0
	v_pk_fma_f32 v[38:39], v[38:39], v[36:37], v[34:35]
	ds_read_b128 v[34:37], v112
	s_waitcnt lgkmcnt(0)
	v_pk_fma_f32 v[22:23], v[22:23], v[34:35], v[38:39]
	s_nop 0
	v_pk_fma_f32 v[34:35], v[24:25], v[36:37], v[22:23]
	ds_read_b128 v[22:25], v113
	s_waitcnt lgkmcnt(0)
	v_pk_fma_f32 v[18:19], v[18:19], v[22:23], v[34:35]
	s_nop 0
	v_pk_fma_f32 v[22:23], v[20:21], v[24:25], v[18:19]
	ds_read_b128 v[18:21], v114
	s_waitcnt lgkmcnt(0)
	v_pk_fma_f32 v[14:15], v[14:15], v[18:19], v[22:23]
	s_nop 0
	v_pk_fma_f32 v[18:19], v[16:17], v[20:21], v[14:15]
	ds_read_b128 v[14:17], v115
	s_waitcnt lgkmcnt(0)
	v_pk_fma_f32 v[10:11], v[10:11], v[14:15], v[18:19]
	s_nop 0
	v_pk_fma_f32 v[14:15], v[12:13], v[16:17], v[10:11]
	ds_read_b128 v[10:13], v116
	s_waitcnt lgkmcnt(0)
	v_pk_fma_f32 v[6:7], v[6:7], v[10:11], v[14:15]
	s_nop 0
	v_pk_fma_f32 v[10:11], v[8:9], v[12:13], v[6:7]
	ds_read_b128 v[6:9], v117
	v_cndmask_b32_e64 v12, v48, v126, s[8:9]
	s_waitcnt lgkmcnt(0)
	v_pk_fma_f32 v[2:3], v[2:3], v[6:7], v[10:11]
	s_nop 0
	v_pk_fma_f32 v[2:3], v[4:5], v[8:9], v[2:3]
	v_xor_b32_e32 v4, 32, v118
	v_add_f32_e32 v3, v2, v3
	v_and_b32_e32 v2, 64, v118
	v_add_u32_e32 v2, 64, v2
	v_cmp_lt_i32_e32 vcc, v4, v2
	v_cndmask_b32_e64 v6, v42, v120, s[8:9]
	v_cndmask_b32_e64 v7, v43, v121, s[8:9]
	v_cndmask_b32_e32 v4, v118, v4, vcc
	v_lshlrev_b32_e32 v4, 2, v4
	ds_bpermute_b32 v6, v4, v6
	ds_bpermute_b32 v7, v4, v7
	v_cndmask_b32_e64 v8, v44, v122, s[8:9]
	ds_bpermute_b32 v8, v4, v8
	v_cndmask_b32_e64 v9, v45, v123, s[8:9]
	ds_bpermute_b32 v9, v4, v9
	v_cndmask_b32_e64 v10, v46, v124, s[8:9]
	v_cndmask_b32_e64 v5, v120, v42, s[8:9]
	ds_bpermute_b32 v10, v4, v10
	v_cndmask_b32_e64 v11, v47, v125, s[8:9]
	s_waitcnt lgkmcnt(4)
	v_add_f32_e32 v5, v5, v6
	v_cndmask_b32_e64 v6, v121, v43, s[8:9]
	ds_bpermute_b32 v11, v4, v11
	s_waitcnt lgkmcnt(4)
	v_add_f32_e32 v6, v6, v7
	v_cndmask_b32_e64 v7, v122, v44, s[8:9]
	ds_bpermute_b32 v12, v4, v12
	s_waitcnt lgkmcnt(4)
	v_add_f32_e32 v7, v7, v8
	v_cndmask_b32_e64 v8, v123, v45, s[8:9]
	s_waitcnt lgkmcnt(3)
	v_add_f32_e32 v8, v8, v9
	v_cndmask_b32_e64 v9, v124, v46, s[8:9]
	s_waitcnt lgkmcnt(2)
	v_add_f32_e32 v9, v9, v10
	v_cndmask_b32_e64 v10, v125, v47, s[8:9]
	s_waitcnt lgkmcnt(1)
	v_add_f32_e32 v10, v10, v11
	v_cndmask_b32_e64 v11, v126, v48, s[8:9]
	s_waitcnt lgkmcnt(0)
	v_add_f32_e32 v11, v11, v12
	v_cndmask_b32_e64 v12, v3, v49, s[8:9]
	v_cndmask_b32_e64 v3, v49, v3, s[8:9]
	ds_bpermute_b32 v3, v4, v3
	v_xor_b32_e32 v4, 16, v118
	v_cmp_lt_i32_e32 vcc, v4, v2
	s_waitcnt lgkmcnt(0)
	v_add_f32_e32 v3, v12, v3
	v_cndmask_b32_e32 v4, v118, v4, vcc
	v_lshlrev_b32_e32 v4, 2, v4
	v_cndmask_b32_e64 v12, v9, v5, s[10:11]
	v_cndmask_b32_e64 v5, v5, v9, s[10:11]
	v_cndmask_b32_e64 v9, v10, v6, s[10:11]
	v_cndmask_b32_e64 v6, v6, v10, s[10:11]
	ds_bpermute_b32 v6, v4, v6
	ds_bpermute_b32 v5, v4, v5
	s_waitcnt lgkmcnt(1)
	v_add_f32_e32 v6, v9, v6
	v_cndmask_b32_e64 v9, v11, v7, s[10:11]
	v_cndmask_b32_e64 v7, v7, v11, s[10:11]
	ds_bpermute_b32 v7, v4, v7
	s_waitcnt lgkmcnt(1)
	v_add_f32_e32 v5, v12, v5
	s_waitcnt lgkmcnt(0)
	v_add_f32_e32 v7, v9, v7
	v_cndmask_b32_e64 v9, v3, v8, s[10:11]
	v_cndmask_b32_e64 v3, v8, v3, s[10:11]
	ds_bpermute_b32 v3, v4, v3
	v_xor_b32_e32 v4, 8, v118
	v_cmp_lt_i32_e32 vcc, v4, v2
	v_cndmask_b32_e64 v8, v7, v5, s[12:13]
	v_cndmask_b32_e64 v5, v5, v7, s[12:13]
	s_waitcnt lgkmcnt(0)
	v_add_f32_e32 v3, v9, v3
	v_cndmask_b32_e32 v4, v118, v4, vcc
	v_lshlrev_b32_e32 v4, 2, v4
	v_cndmask_b32_e64 v7, v3, v6, s[12:13]
	v_cndmask_b32_e64 v3, v6, v3, s[12:13]
	ds_bpermute_b32 v5, v4, v5
	ds_bpermute_b32 v3, v4, v3
	s_waitcnt lgkmcnt(1)
	v_add_f32_e32 v5, v8, v5
	s_waitcnt lgkmcnt(0)
	v_add_f32_e32 v3, v7, v3
	v_cndmask_b32_e64 v4, v3, v5, s[14:15]
	v_cndmask_b32_e64 v3, v5, v3, s[14:15]
	v_xor_b32_e32 v5, 4, v118
	v_cmp_lt_i32_e32 vcc, v5, v2
	s_nop 1
	v_cndmask_b32_e32 v5, v118, v5, vcc
	v_lshlrev_b32_e32 v5, 2, v5
	ds_bpermute_b32 v3, v5, v3
	s_waitcnt lgkmcnt(0)
	v_add_f32_e32 v3, v4, v3
	v_xor_b32_e32 v4, 2, v118
	v_cmp_lt_i32_e32 vcc, v4, v2
	s_nop 1
	v_cndmask_b32_e32 v4, v118, v4, vcc
	v_lshlrev_b32_e32 v4, 2, v4
	ds_bpermute_b32 v4, v4, v3
	s_waitcnt lgkmcnt(0)
	v_add_f32_e32 v3, v3, v4
	v_xor_b32_e32 v4, 1, v118
	v_cmp_lt_i32_e32 vcc, v4, v2
	s_nop 1
	v_cndmask_b32_e32 v2, v118, v4, vcc
	v_lshlrev_b32_e32 v2, 2, v2
	ds_bpermute_b32 v2, v2, v3
	s_and_saveexec_b64 s[30:31], s[16:17]
	s_cbranch_execz .LBB0_94
	s_load_dwordx2 s[34:35], s[6:7], 0x68
	s_waitcnt lgkmcnt(0)
	v_add_f32_e32 v2, v3, v2
	global_load_dword v4, v84, s[34:35]
	s_lshl_b64 s[34:35], s[20:21], 5
	s_waitcnt vmcnt(0)
	v_add_f32_e32 v4, v2, v4
	s_and_saveexec_b64 s[20:21], s[18:19]
	s_xor_b64 s[36:37], exec, s[20:21]
	s_cbranch_execz .LBB0_100
	v_mul_f32_e64 v2, |v4|, s49
	v_exp_f32_e32 v5, v2
	v_max_f32_e32 v4, v4, v4
	v_lshl_add_u64 v[2:3], v[26:27], 0, s[34:35]
	v_min_f32_e32 v4, 0, v4
	v_add_f32_e32 v5, 1.0, v5
	v_cmp_gt_f32_e32 vcc, s50, v5
	v_lshl_add_u64 v[2:3], v[2:3], 0, s[28:29]
	s_nop 0
	v_cndmask_b32_e64 v6, 0, 32, vcc
	v_ldexp_f32 v5, v5, v6
	v_log_f32_e32 v5, v5
	s_nop 0
	v_mul_f32_e32 v6, 0x3f317217, v5
	v_fma_f32 v6, v5, s51, -v6
	v_fmac_f32_e32 v6, 0x3377d1cf, v5
	v_fmac_f32_e32 v6, 0x3f317217, v5
	v_cmp_lt_f32_e64 s[20:21], |v5|, s52
	s_nop 1
	v_cndmask_b32_e64 v5, v5, v6, s[20:21]
	v_cndmask_b32_e32 v6, 0, v119, vcc
	v_sub_f32_e32 v5, v5, v6
	v_sub_f32_e32 v4, v4, v5

.LBB0_1034:
	s_or_b64 exec, exec, s[8:9]
	s_add_u32 s62, s88, 0xee19000
	s_addc_u32 s63, s89, 0
	s_lshl_b32 s8, s96, 2
	v_readlane_b32 s9, v253, 16
	s_add_i32 s8, s9, s8
	s_lshl_b32 s10, s8, 3
	s_and_b32 s55, s10, 0x7fffffc0
	v_readlane_b32 s10, v253, 19
	v_lshlrev_b32_e32 v12, 4, v1
	s_and_b32 s9, s8, 7
	v_add_u32_e32 v7, s10, v1
	v_ashrrev_i32_e32 v10, 4, v7
	v_and_b32_e32 v82, 0xf0, v12
	v_readlane_b32 s10, v253, 18
	v_add_u32_e32 v2, s55, v10
	v_mov_b64_e32 v[8:9], s[62:63]
	v_add_u32_e32 v6, s10, v82
	v_mad_i64_i32 v[2:3], s[10:11], v2, s83, v[8:9]
	s_lshl_b32 s70, s9, 8
	v_lshl_add_u64 v[2:3], v[2:3], 0, s[70:71]
	v_lshl_add_u64 v[2:3], v[2:3], 0, v[82:83]
	s_barrier
	s_mov_b64 s[84:85], 0x18000
	global_load_dwordx4 v[180:183], v[2:3], off offset:2048
	v_lshl_add_u64 v[2:3], v[2:3], 0, s[84:85]
	global_load_dwordx4 v[184:187], v[2:3], off offset:2048
	v_lshl_add_u64 v[2:3], v[2:3], 0, s[84:85]
	global_load_dwordx4 v[188:191], v[2:3], off offset:2048
	v_lshl_add_u64 v[2:3], v[2:3], 0, s[84:85]
	global_load_dwordx4 v[192:195], v[2:3], off offset:2048
	v_lshl_add_u64 v[2:3], v[2:3], 0, s[84:85]
	global_load_dwordx4 v[196:199], v[2:3], off offset:2048
	v_lshl_add_u64 v[2:3], v[2:3], 0, s[84:85]
	global_load_dwordx4 v[200:203], v[2:3], off offset:2048
	v_lshl_add_u64 v[2:3], v[2:3], 0, s[84:85]
	global_load_dwordx4 v[204:207], v[2:3], off offset:2048
	v_lshl_add_u64 v[2:3], v[2:3], 0, s[84:85]
	global_load_dwordx4 v[208:211], v[2:3], off offset:2048
	v_mad_u64_u32 v[10:11], s[10:11], v10, s5, v[6:7]
	s_lshl_b32 s54, s9, 7
	s_mov_b32 s9, s71
	s_waitcnt vmcnt(10)
	v_and_b32_e32 v138, 31, v1
	v_readlane_b32 s14, v253, 17
	s_mul_i32 s13, s8, 0x300
	s_load_dwordx2 s[64:65], s[40:41], 0x70
	v_or_b32_e32 v141, s14, v138
	s_mul_hi_u32 s12, s8, 0x300
	v_ashrrev_i32_e32 v143, 5, v1
	v_lshlrev_b32_e32 v134, 2, v143
	s_movk_i32 s61, 0x440
	v_ashrrev_i32_e32 v135, 31, v134
	s_mov_b32 s60, 0
	v_mov_b32_e32 v146, 0
	s_lshl_b64 s[10:11], s[8:9], 2
	s_add_u32 s10, s88, s10
	s_addc_u32 s11, s89, s11
	s_add_u32 s40, s88, s13
	v_lshlrev_b32_e32 v82, 2, v141
	s_addc_u32 s41, s89, s12
	s_mov_b32 s9, 0x1519d000
	s_waitcnt vmcnt(7)
	ds_write_b128 v10, v[180:183]
	s_waitcnt vmcnt(6)
	ds_write_b128 v10, v[184:187] offset:2176
	s_waitcnt vmcnt(5)
	ds_write_b128 v10, v[188:191] offset:4352
	s_waitcnt vmcnt(4)
	ds_write_b128 v10, v[192:195] offset:6528
	s_waitcnt vmcnt(3)
	ds_write_b128 v10, v[196:199] offset:8704
	s_waitcnt vmcnt(2)
	ds_write_b128 v10, v[200:203] offset:10880
	s_waitcnt vmcnt(1)
	ds_write_b128 v10, v[204:207] offset:13056
	s_waitcnt vmcnt(0)
	ds_write_b128 v10, v[208:211] offset:15232
	v_mov_b32_e32 v2, 0x1869d000
	global_load_dword v6, v2, s[10:11]
	v_lshl_add_u64 v[2:3], s[40:41], 0, v[82:83]
	s_mov_b64 s[10:11], 0x1519d000
	v_lshl_add_u64 v[4:5], v[2:3], 0, s[10:11]
	v_add_co_u32_e32 v2, vcc, s9, v2
	s_add_u32 s10, s62, s54
	s_nop 0
	v_addc_co_u32_e32 v3, vcc, 0, v3, vcc
	global_load_dword v139, v[2:3], off
	s_nop 0
	global_load_dword v2, v[4:5], off offset:512
	s_addc_u32 s11, s63, 0
	v_and_b32_e32 v82, 0x70, v12
	v_lshl_add_u64 v[132:133], s[10:11], 0, v[82:83]
	v_readlane_b32 s9, v253, 20
	s_waitcnt vmcnt(2)
	v_max_f32_e32 v3, v6, v6
	v_add_u32_e32 v20, s9, v82
	s_waitcnt vmcnt(0)
	v_max_f32_e32 v2, v2, v2
	v_max_f32_e32 v140, v3, v2
	v_sub_f32_e32 v2, v6, v140
	v_mul_f32_e32 v3, 0x3fb8aa3b, v2
	v_ashrrev_i32_e32 v2, 3, v1
	v_add_u32_e32 v142, s55, v2
	v_add_u32_e32 v16, s14, v142
	v_mad_i64_i32 v[4:5], s[10:11], v16, s83, v[132:133]
	v_add_u32_e32 v8, 8, v16
	global_load_dwordx4 v[4:7], v[4:5], off
	v_mad_i64_i32 v[8:9], s[10:11], v8, s83, v[132:133]
	v_add_u32_e32 v12, 16, v16
	global_load_dwordx4 v[8:11], v[8:9], off
	v_mad_i64_i32 v[12:13], s[10:11], v12, s83, v[132:133]
	v_add_u32_e32 v16, 24, v16
	global_load_dwordx4 v[12:15], v[12:13], off
	v_mad_i64_i32 v[16:17], s[10:11], v16, s83, v[132:133]
	global_load_dwordx4 v[16:19], v[16:17], off
	s_movk_i32 s10, 0x90
	v_mul_lo_u32 v21, v2, s10
	v_add_u32_e32 v144, v20, v21
	s_waitcnt vmcnt(3)
	ds_write_b128 v144, v[4:7]
	s_waitcnt vmcnt(2)
	ds_write_b128 v144, v[8:11] offset:1152
	s_waitcnt vmcnt(1)
	ds_write_b128 v144, v[12:15] offset:2304
	s_waitcnt vmcnt(0)
	ds_write_b128 v144, v[16:19] offset:3456
	v_exp_f32_e32 v4, v3
	v_mov_b32_e32 v3, s9
	v_mad_u32_u24 v3, v138, s10, v3
	v_lshlrev_b32_e32 v5, 4, v143
	s_waitcnt lgkmcnt(0)
	v_add_u32_e32 v145, v3, v5
	ds_read_b128 v[96:99], v145
	ds_read_b128 v[104:107], v145 offset:32
	ds_read_b128 v[108:111], v145 offset:64
	ds_read_b128 v[112:115], v145 offset:96
	s_mul_hi_u32 s9, s8, 0x5000
	s_waitcnt lgkmcnt(0)
	v_and_b32_e32 v9, 0xffff0000, v97
	v_and_b32_e32 v8, 0xffff0000, v96
	v_and_b32_e32 v13, 0xffff0000, v99
	v_and_b32_e32 v12, 0xffff0000, v98
	v_lshlrev_b32_e32 v7, 16, v97
	v_lshlrev_b32_e32 v6, 16, v96
	v_pk_mul_f32 v[8:9], v[4:5], v[8:9] op_sel_hi:[0,1]
	v_lshlrev_b32_e32 v11, 16, v99
	v_lshlrev_b32_e32 v10, 16, v98
	v_pk_mul_f32 v[12:13], v[4:5], v[12:13] op_sel_hi:[0,1]
	v_pk_mul_f32 v[6:7], v[4:5], v[6:7] op_sel_hi:[0,1]
	v_pk_mul_f32 v[10:11], v[4:5], v[10:11] op_sel_hi:[0,1]
	v_bfe_u32 v3, v13, 16, 1
	v_bfe_u32 v5, v12, 16, 1
	v_add3_u32 v5, v12, v5, s73
	v_add3_u32 v3, v13, v3, s73
	v_bfe_u32 v14, v10, 16, 1
	v_bfe_u32 v15, v11, 16, 1
	v_add3_u32 v11, v11, v15, s73
	v_add3_u32 v10, v10, v14, s73
	v_lshrrev_b32_e32 v10, 16, v10
	v_lshrrev_b32_e32 v11, 16, v11
	v_and_b32_e32 v13, 0xffff0000, v107
	v_and_b32_e32 v12, 0xffff0000, v106
	v_and_or_b32 v91, v3, s33, v11
	v_and_or_b32 v90, v5, s33, v10
	v_cvt_pk_bf16_f32 v89, v7, v9
	v_cvt_pk_bf16_f32 v88, v6, v8
	v_lshlrev_b32_e32 v7, 16, v105
	v_lshlrev_b32_e32 v6, 16, v104
	v_and_b32_e32 v9, 0xffff0000, v105
	v_and_b32_e32 v8, 0xffff0000, v104
	v_lshlrev_b32_e32 v11, 16, v107
	v_lshlrev_b32_e32 v10, 16, v106
	v_pk_mul_f32 v[12:13], v[4:5], v[12:13] op_sel_hi:[0,1]
	v_pk_mul_f32 v[6:7], v[4:5], v[6:7] op_sel_hi:[0,1]
	v_pk_mul_f32 v[8:9], v[4:5], v[8:9] op_sel_hi:[0,1]
	v_pk_mul_f32 v[10:11], v[4:5], v[10:11] op_sel_hi:[0,1]
	v_bfe_u32 v3, v13, 16, 1
	v_bfe_u32 v5, v12, 16, 1
	v_add3_u32 v5, v12, v5, s73
	v_add3_u32 v3, v13, v3, s73
	v_bfe_u32 v14, v10, 16, 1
	v_bfe_u32 v15, v11, 16, 1
	v_add3_u32 v11, v11, v15, s73
	v_add3_u32 v10, v10, v14, s73
	v_lshrrev_b32_e32 v10, 16, v10
	v_lshrrev_b32_e32 v11, 16, v11
	v_cvt_pk_bf16_f32 v85, v7, v9
	v_cvt_pk_bf16_f32 v84, v6, v8
	v_and_b32_e32 v9, 0xffff0000, v109
	v_and_b32_e32 v8, 0xffff0000, v108
	v_and_b32_e32 v13, 0xffff0000, v111
	v_and_b32_e32 v12, 0xffff0000, v110
	v_and_or_b32 v87, v3, s33, v11
	v_and_or_b32 v86, v5, s33, v10
	v_lshlrev_b32_e32 v7, 16, v109
	v_lshlrev_b32_e32 v6, 16, v108
	v_pk_mul_f32 v[8:9], v[4:5], v[8:9] op_sel_hi:[0,1]
	v_lshlrev_b32_e32 v11, 16, v111
	v_lshlrev_b32_e32 v10, 16, v110
	v_pk_mul_f32 v[12:13], v[4:5], v[12:13] op_sel_hi:[0,1]
	v_pk_mul_f32 v[6:7], v[4:5], v[6:7] op_sel_hi:[0,1]
	v_pk_mul_f32 v[10:11], v[4:5], v[10:11] op_sel_hi:[0,1]
	v_bfe_u32 v3, v13, 16, 1
	v_bfe_u32 v5, v12, 16, 1
	v_add3_u32 v5, v12, v5, s73
	v_add3_u32 v3, v13, v3, s73
	v_bfe_u32 v14, v10, 16, 1
	v_bfe_u32 v15, v11, 16, 1
	v_add3_u32 v11, v11, v15, s73
	v_add3_u32 v10, v10, v14, s73
	v_lshrrev_b32_e32 v10, 16, v10
	v_lshrrev_b32_e32 v11, 16, v11
	v_and_or_b32 v95, v3, s33, v11
	v_and_or_b32 v94, v5, s33, v10
	v_cvt_pk_bf16_f32 v93, v7, v9
	v_cvt_pk_bf16_f32 v92, v6, v8
	v_lshlrev_b32_e32 v7, 16, v113
	v_lshlrev_b32_e32 v6, 16, v112
	v_and_b32_e32 v9, 0xffff0000, v113
	v_and_b32_e32 v8, 0xffff0000, v112
	v_lshlrev_b32_e32 v11, 16, v115
	v_lshlrev_b32_e32 v10, 16, v114
	v_and_b32_e32 v13, 0xffff0000, v115
	v_and_b32_e32 v12, 0xffff0000, v114
	v_pk_mul_f32 v[6:7], v[4:5], v[6:7] op_sel_hi:[0,1]
	v_pk_mul_f32 v[8:9], v[4:5], v[8:9] op_sel_hi:[0,1]
	v_pk_mul_f32 v[10:11], v[4:5], v[10:11] op_sel_hi:[0,1]
	v_pk_mul_f32 v[4:5], v[4:5], v[12:13] op_sel_hi:[0,1]
	v_bfe_u32 v12, v4, 16, 1
	v_bfe_u32 v13, v9, 16, 1
	v_bfe_u32 v14, v8, 16, 1
	v_bfe_u32 v3, v5, 16, 1
	v_add3_u32 v8, v8, v14, s73
	v_add3_u32 v9, v9, v13, s73
	v_add3_u32 v4, v4, v12, s73
	v_bfe_u32 v12, v7, 16, 1
	v_bfe_u32 v13, v10, 16, 1
	v_bfe_u32 v14, v11, 16, 1
	v_add3_u32 v3, v5, v3, s73
	v_bfe_u32 v5, v6, 16, 1
	v_add3_u32 v11, v11, v14, s73
	v_add3_u32 v10, v10, v13, s73
	v_add3_u32 v7, v7, v12, s73
	s_mulk_i32 s8, 0x5000
	v_add3_u32 v5, v6, v5, s73
	v_lshrrev_b32_e32 v6, 16, v7
	v_lshrrev_b32_e32 v7, 16, v10
	v_lshrrev_b32_e32 v10, 16, v11
	s_add_u32 s8, s88, s8
	v_lshrrev_b32_e32 v5, 16, v5
	v_and_or_b32 v103, v3, s33, v10
	s_addc_u32 s9, s89, s9
	v_ashrrev_i32_e32 v3, 31, v2
	v_and_or_b32 v102, v4, s33, v7
	v_and_or_b32 v100, v8, s33, v5
	v_lshl_add_u64 v[4:5], s[8:9], 0, v[82:83]
	v_lshlrev_b64 v[2:3], 7, v[2:3]
	v_lshl_add_u64 v[66:67], v[4:5], 0, v[2:3]
	s_mov_b64 s[8:9], 0x1729d000
	v_lshl_add_u64 v[14:15], v[66:67], 0, s[8:9]
	s_mov_b32 s8, 0x1729e000
	v_add_co_u32_e32 v30, vcc, s8, v66
	v_and_or_b32 v101, v9, s33, v6
	s_nop 0
	v_addc_co_u32_e32 v31, vcc, 0, v67, vcc
	global_load_dwordx4 v[180:183], v[30:31], off offset:-4096
	global_load_dwordx4 v[184:187], v[14:15], off offset:1024
	global_load_dwordx4 v[188:191], v[14:15], off offset:2048
	global_load_dwordx4 v[192:195], v[14:15], off offset:3072
	global_load_dwordx4 v[196:199], v[30:31], off
	global_load_dwordx4 v[200:203], v[30:31], off offset:1024
	global_load_dwordx4 v[204:207], v[30:31], off offset:2048
	global_load_dwordx4 v[208:211], v[30:31], off offset:3072
	s_waitcnt vmcnt(0)
	s_nop 1
	v_mov_b64_e32 v[2:3], v[180:181]
	v_mov_b64_e32 v[4:5], v[182:183]
	s_nop 1
	v_mov_b64_e32 v[6:7], v[184:185]
	v_mov_b64_e32 v[8:9], v[186:187]
	s_nop 1
	v_mov_b64_e32 v[10:11], v[188:189]
	v_mov_b64_e32 v[12:13], v[190:191]
	s_nop 0
	s_nop 1
	v_mov_b64_e32 v[14:15], v[192:193]
	v_mov_b64_e32 v[16:17], v[194:195]
	s_nop 0
	ds_write_b128 v144, v[2:5]
	s_nop 0
	ds_write_b128 v144, v[6:9] offset:1152
	s_nop 0
	ds_write_b128 v144, v[10:13] offset:2304
	s_nop 0
	ds_write_b128 v144, v[14:17] offset:3456
	s_waitcnt lgkmcnt(0)
	ds_read_b128 v[2:5], v145
	ds_read_b128 v[18:21], v145 offset:32
	s_waitcnt lgkmcnt(1)
	v_mfma_f32_32x32x16_bf16 v[2:17], v[2:5], v[88:91], 0
	s_mov_b32 s8, 0x1729f000
	v_add_co_u32_e32 v46, vcc, s8, v66
	s_mov_b32 s8, 0x172a0000
	s_nop 0
	v_addc_co_u32_e32 v47, vcc, 0, v67, vcc
	v_add_co_u32_e32 v62, vcc, s8, v66
	s_waitcnt lgkmcnt(0)
	v_mfma_f32_32x32x16_bf16 v[2:17], v[18:21], v[84:87], v[2:17]
	ds_read_b128 v[18:21], v145 offset:64
	v_addc_co_u32_e32 v63, vcc, 0, v67, vcc
	s_mov_b32 s8, 0x172a1000
	v_add_co_u32_e32 v78, vcc, s8, v66
	v_cmp_lt_i32_e64 s[8:9], v134, v138
	s_waitcnt lgkmcnt(0)
	v_mfma_f32_32x32x16_bf16 v[2:17], v[18:21], v[92:95], v[2:17]
	ds_read_b128 v[18:21], v145 offset:96
	v_addc_co_u32_e32 v79, vcc, 0, v67, vcc
	v_cmp_le_i32_e32 vcc, v134, v138
	s_waitcnt lgkmcnt(0)
	v_mfma_f32_32x32x16_bf16 v[2:17], v[18:21], v[100:103], v[2:17]
	s_nop 1
	v_mov_b64_e32 v[18:19], v[196:197]
	v_mov_b64_e32 v[20:21], v[198:199]
	s_nop 1
	v_mov_b64_e32 v[22:23], v[200:201]
	v_mov_b64_e32 v[24:25], v[202:203]
	s_nop 1
	v_mov_b64_e32 v[26:27], v[204:205]
	v_mov_b64_e32 v[28:29], v[206:207]
	s_nop 0
	s_nop 1
	v_mov_b64_e32 v[30:31], v[208:209]
	v_mov_b64_e32 v[32:33], v[210:211]
	s_nop 0
	ds_write_b128 v144, v[18:21]
	s_nop 0
	ds_write_b128 v144, v[22:25] offset:1152
	s_nop 0
	ds_write_b128 v144, v[26:29] offset:2304
	s_nop 0
	ds_write_b128 v144, v[30:33] offset:3456
	s_waitcnt lgkmcnt(0)
	ds_read_b128 v[18:21], v145
	ds_read_b128 v[34:37], v145 offset:32
	s_waitcnt lgkmcnt(1)
	v_mfma_f32_32x32x16_bf16 v[18:33], v[18:21], v[88:91], 0
	s_waitcnt lgkmcnt(0)
	v_mfma_f32_32x32x16_bf16 v[18:33], v[34:37], v[84:87], v[18:33]
	ds_read_b128 v[34:37], v145 offset:64
	s_waitcnt lgkmcnt(0)
	v_mfma_f32_32x32x16_bf16 v[18:33], v[34:37], v[92:95], v[18:33]
	ds_read_b128 v[34:37], v145 offset:96
	s_waitcnt lgkmcnt(0)
	v_mfma_f32_32x32x16_bf16 v[18:33], v[34:37], v[100:103], v[18:33]
	global_load_dwordx4 v[180:183], v[62:63], off offset:-4096
	global_load_dwordx4 v[184:187], v[46:47], off offset:1024
	global_load_dwordx4 v[188:191], v[46:47], off offset:2048
	global_load_dwordx4 v[192:195], v[46:47], off offset:3072
	global_load_dwordx4 v[196:199], v[62:63], off
	global_load_dwordx4 v[200:203], v[62:63], off offset:1024
	global_load_dwordx4 v[204:207], v[62:63], off offset:2048
	global_load_dwordx4 v[208:211], v[62:63], off offset:3072
	global_load_dwordx4 v[212:215], v[78:79], off
	global_load_dwordx4 v[216:219], v[78:79], off offset:1024
	global_load_dwordx4 v[220:223], v[78:79], off offset:2048
	global_load_dwordx4 v[236:239], v[78:79], off offset:3072
	s_waitcnt vmcnt(0)
	s_nop 1
	v_mov_b64_e32 v[34:35], v[180:181]
	v_mov_b64_e32 v[36:37], v[182:183]
	s_nop 1
	v_mov_b64_e32 v[38:39], v[184:185]
	v_mov_b64_e32 v[40:41], v[186:187]
	s_nop 1
	v_mov_b64_e32 v[42:43], v[188:189]
	v_mov_b64_e32 v[44:45], v[190:191]
	s_nop 0
	s_nop 1
	v_mov_b64_e32 v[46:47], v[192:193]
	v_mov_b64_e32 v[48:49], v[194:195]
	s_nop 0
	ds_write_b128 v144, v[34:37]
	s_nop 0
	ds_write_b128 v144, v[38:41] offset:1152
	s_nop 0
	ds_write_b128 v144, v[42:45] offset:2304
	s_nop 0
	ds_write_b128 v144, v[46:49] offset:3456
	s_waitcnt lgkmcnt(0)
	ds_read_b128 v[34:37], v145
	ds_read_b128 v[50:53], v145 offset:32
	s_waitcnt lgkmcnt(1)
	v_mfma_f32_32x32x16_bf16 v[34:49], v[34:37], v[88:91], 0
	s_waitcnt lgkmcnt(0)
	v_mfma_f32_32x32x16_bf16 v[34:49], v[50:53], v[84:87], v[34:49]
	ds_read_b128 v[50:53], v145 offset:64
	s_waitcnt lgkmcnt(0)
	v_mfma_f32_32x32x16_bf16 v[34:49], v[50:53], v[92:95], v[34:49]
	ds_read_b128 v[50:53], v145 offset:96
	s_waitcnt lgkmcnt(0)
	v_mfma_f32_32x32x16_bf16 v[34:49], v[50:53], v[100:103], v[34:49]
	s_nop 1
	v_mov_b64_e32 v[50:51], v[196:197]
	v_mov_b64_e32 v[52:53], v[198:199]
	s_nop 1
	v_mov_b64_e32 v[54:55], v[200:201]
	v_mov_b64_e32 v[56:57], v[202:203]
	s_nop 1
	v_mov_b64_e32 v[58:59], v[204:205]
	v_mov_b64_e32 v[60:61], v[206:207]
	s_nop 0
	s_nop 1
	v_mov_b64_e32 v[62:63], v[208:209]
	v_mov_b64_e32 v[64:65], v[210:211]
	s_nop 0
	ds_write_b128 v144, v[50:53]
	s_nop 0
	ds_write_b128 v144, v[54:57] offset:1152
	s_nop 0
	ds_write_b128 v144, v[58:61] offset:2304
	s_nop 0
	ds_write_b128 v144, v[62:65] offset:3456
	s_waitcnt lgkmcnt(0)
	ds_read_b128 v[50:53], v145
	ds_read_b128 v[68:71], v145 offset:32
	s_waitcnt lgkmcnt(1)
	v_mfma_f32_32x32x16_bf16 v[50:65], v[50:53], v[88:91], 0
	s_waitcnt lgkmcnt(0)
	v_mfma_f32_32x32x16_bf16 v[50:65], v[68:71], v[84:87], v[50:65]
	ds_read_b128 v[68:71], v145 offset:64
	s_waitcnt lgkmcnt(0)
	v_mfma_f32_32x32x16_bf16 v[50:65], v[68:71], v[92:95], v[50:65]
	ds_read_b128 v[68:71], v145 offset:96
	s_waitcnt lgkmcnt(0)
	v_mfma_f32_32x32x16_bf16 v[50:65], v[68:71], v[100:103], v[50:65]
	s_nop 1
	v_mov_b64_e32 v[66:67], v[212:213]
	v_mov_b64_e32 v[68:69], v[214:215]
	s_nop 1
	v_mov_b64_e32 v[70:71], v[216:217]
	v_mov_b64_e32 v[72:73], v[218:219]
	s_nop 1
	v_mov_b64_e32 v[74:75], v[220:221]
	v_mov_b64_e32 v[76:77], v[222:223]
	s_nop 0
	s_nop 1
	v_mov_b64_e32 v[78:79], v[236:237]
	v_mov_b64_e32 v[80:81], v[238:239]
	s_nop 0
	ds_write_b128 v144, v[66:69]
	s_nop 0
	ds_write_b128 v144, v[70:73] offset:1152
	s_nop 0
	ds_write_b128 v144, v[74:77] offset:2304
	s_nop 0
	ds_write_b128 v144, v[78:81] offset:3456
	v_add_u32_e32 v66, 8, v134
	v_cmp_le_i32_e64 s[14:15], v66, v138
	v_add_u32_e32 v66, 9, v134
	v_cmp_le_i32_e64 s[16:17], v66, v138
	v_add_u32_e32 v66, 10, v134
	v_cmp_le_i32_e64 s[18:19], v66, v138
	v_add_u32_e32 v66, 11, v134
	v_cmp_le_i32_e64 s[20:21], v66, v138
	v_add_u32_e32 v66, 17, v134
	v_cmp_le_i32_e64 s[24:25], v66, v138
	v_add_u32_e32 v66, 18, v134
	v_cmp_le_i32_e64 s[26:27], v66, v138
	v_add_u32_e32 v66, 19, v134
	s_waitcnt lgkmcnt(0)
	v_cmp_le_i32_e64 s[28:29], v66, v138
	v_add_u32_e32 v66, 25, v134
	ds_read_b128 v[128:131], v145
	ds_read_b128 v[124:127], v145 offset:32
	ds_read_b128 v[120:123], v145 offset:64
	ds_read_b128 v[116:119], v145 offset:96
	v_cmp_le_i32_e64 s[34:35], v66, v138
	v_add_u32_e32 v66, 26, v134
	v_bfe_u32 v67, v1, 2, 2
	v_cmp_le_i32_e64 s[36:37], v66, v138
	v_add_u32_e32 v66, 27, v134
	v_cmp_le_i32_e64 s[38:39], v66, v138
	v_mul_lo_u32 v66, v143, s61
	v_mul_u32_u24_e32 v67, 0x110, v67
	v_readlane_b32 s61, v253, 60
	v_or_b32_e32 v70, 2, v134
	v_add_u32_e32 v68, 16, v134
	v_add3_u32 v66, s61, v66, v67
	v_lshlrev_b32_e32 v67, 1, v1
	v_and_b32_e32 v1, 3, v1
	v_and_b32_e32 v67, 32, v67
	v_lshlrev_b32_e32 v1, 3, v1
	v_add_u32_e32 v69, 24, v134
	v_cmp_le_i32_e64 s[10:11], v70, v138
	v_or_b32_e32 v70, 3, v134
	v_add3_u32 v1, v66, v67, v1
	v_lshl_add_u64 v[66:67], v[134:135], 2, s[40:41]
	s_mov_b64 s[40:41], 0x1519d160
	v_cmp_le_i32_e64 s[12:13], v70, v138
	v_cmp_le_i32_e64 s[22:23], v68, v138
	v_cmp_le_i32_e64 s[30:31], v69, v138
	v_lshl_add_u64 v[136:137], v[66:67], 0, s[40:41]
	s_mov_b32 s61, 0
	s_waitcnt lgkmcnt(0)
	s_barrier

.LBB0_1222:
	s_abs_i32 s10, s8
	v_readlane_b32 s11, v253, 56
	s_mul_hi_u32 s11, s10, s11
	v_readlane_b32 s18, v253, 57
	s_mul_i32 s16, s11, s18
	s_ashr_i32 s9, s8, 31
	s_sub_i32 s10, s10, s16
	s_xor_b32 s9, s9, s43
	s_add_i32 s16, s11, 1
	s_sub_i32 s17, s10, s18
	s_cmp_ge_u32 s10, s18
	s_cselect_b32 s11, s16, s11
	s_cselect_b32 s10, s17, s10
	s_add_i32 s16, s11, 1
	s_cmp_ge_u32 s10, s18
	s_cselect_b32 s10, s16, s11
	s_xor_b32 s10, s10, s9
	s_sub_i32 s9, s10, s9
	s_add_i32 s9, s8, s9
	s_and_b32 s9, s9, 7
	v_readlane_b32 s10, v253, 15
	s_cmp_lg_u32 s10, s9
	s_cbranch_scc1 .LBB0_1221
	s_lshr_b32 s9, s8, 3
	s_add_i32 s16, s8, 0x2000
	s_add_i32 s9, s9, 1
	s_cmp_gt_i32 s8, -1
	s_cselect_b32 s9, s9, 0
	s_add_i32 s9, s9, s97
	s_mul_hi_u32 s11, s9, 0xc000
	s_mul_i32 s9, s9, 0xc000
	s_add_u32 s10, s26, s9
	v_lshl_add_u64 v[2:3], s[14:15], 0, v[12:13]
	s_mov_b32 s9, 0x3af5e000
	v_add_co_u32_e32 v8, vcc, s9, v2
	s_mov_b32 s9, 0x3af5f000
	s_nop 0
	v_addc_co_u32_e32 v9, vcc, 0, v3, vcc
	v_add_co_u32_e32 v62, vcc, s9, v2
	s_mov_b32 s9, 0x3b15e000
	s_nop 0
	v_addc_co_u32_e32 v63, vcc, 0, v3, vcc
	global_load_dwordx4 v[4:7], v[62:63], off offset:-4096
	global_load_dwordx4 v[38:41], v[8:9], off offset:1024
	global_load_dwordx4 v[42:45], v[8:9], off offset:2048
	global_load_dwordx4 v[46:49], v[8:9], off offset:3072
	global_load_dwordx4 v[50:53], v[62:63], off
	global_load_dwordx4 v[54:57], v[62:63], off offset:1024
	global_load_dwordx4 v[58:61], v[62:63], off offset:2048
	s_nop 0
	global_load_dwordx4 v[62:65], v[62:63], off offset:3072
	v_add_co_u32_e32 v8, vcc, s9, v2
	s_mov_b32 s9, 0x3b15f000
	s_nop 0
	v_addc_co_u32_e32 v9, vcc, 0, v3, vcc
	v_add_co_u32_e32 v96, vcc, s9, v2
	s_mov_b32 s9, 0x3b35e000
	s_nop 0
	v_addc_co_u32_e32 v97, vcc, 0, v3, vcc
	global_load_dwordx4 v[66:69], v[96:97], off offset:-4096
	global_load_dwordx4 v[70:73], v[8:9], off offset:1024
	global_load_dwordx4 v[74:77], v[8:9], off offset:2048
	global_load_dwordx4 v[78:81], v[8:9], off offset:3072
	global_load_dwordx4 v[84:87], v[96:97], off
	global_load_dwordx4 v[88:91], v[96:97], off offset:1024
	global_load_dwordx4 v[92:95], v[96:97], off offset:2048
	s_nop 0
	global_load_dwordx4 v[96:99], v[96:97], off offset:3072
	v_add_co_u32_e32 v8, vcc, s9, v2
	s_mov_b32 s9, 0x3b35f000
	s_nop 0
	v_addc_co_u32_e32 v9, vcc, 0, v3, vcc
	v_add_co_u32_e32 v128, vcc, s9, v2
	s_mov_b32 s9, 0x3b55e000
	s_nop 0
	v_addc_co_u32_e32 v129, vcc, 0, v3, vcc
	global_load_dwordx4 v[100:103], v[128:129], off offset:-4096
	global_load_dwordx4 v[104:107], v[8:9], off offset:1024
	global_load_dwordx4 v[108:111], v[8:9], off offset:2048
	global_load_dwordx4 v[112:115], v[8:9], off offset:3072
	global_load_dwordx4 v[116:119], v[128:129], off
	global_load_dwordx4 v[120:123], v[128:129], off offset:1024
	global_load_dwordx4 v[124:127], v[128:129], off offset:2048
	s_nop 0
	global_load_dwordx4 v[128:131], v[128:129], off offset:3072
	s_addc_u32 s11, s27, s11
	s_ashr_i32 s17, s16, 31
	s_waitcnt vmcnt(15)
	v_pk_add_f32 v[6:7], v[6:7], v[68:69]
	s_waitcnt vmcnt(14)
	v_pk_add_f32 v[8:9], v[40:41], v[72:73]
	s_waitcnt vmcnt(13)
	v_pk_add_f32 v[42:43], v[42:43], v[74:75]
	v_pk_add_f32 v[40:41], v[44:45], v[76:77]
	s_waitcnt vmcnt(12)
	v_pk_add_f32 v[44:45], v[48:49], v[80:81]
	s_waitcnt vmcnt(11)
	v_pk_add_f32 v[48:49], v[52:53], v[86:87]
	s_waitcnt vmcnt(10)
	v_pk_add_f32 v[52:53], v[56:57], v[90:91]
	s_waitcnt vmcnt(9)
	v_pk_add_f32 v[56:57], v[60:61], v[94:95]
	s_waitcnt vmcnt(8)
	v_pk_add_f32 v[60:61], v[64:65], v[98:99]
	v_pk_add_f32 v[58:59], v[58:59], v[92:93]
	v_pk_add_f32 v[4:5], v[4:5], v[66:67]
	v_pk_add_f32 v[38:39], v[38:39], v[70:71]
	v_pk_add_f32 v[50:51], v[50:51], v[84:85]
	s_waitcnt vmcnt(5)
	v_pk_add_f32 v[74:75], v[42:43], v[108:109]
	v_add_co_u32_e32 v42, vcc, s9, v2
	s_mov_b32 s9, 0x3b55f000
	s_nop 0
	v_addc_co_u32_e32 v43, vcc, 0, v3, vcc
	s_waitcnt vmcnt(0)
	v_pk_add_f32 v[92:93], v[60:61], v[130:131]
	v_add_co_u32_e32 v60, vcc, s9, v2
	v_pk_add_f32 v[54:55], v[54:55], v[88:89]
	v_pk_add_f32 v[62:63], v[62:63], v[96:97]
	v_addc_co_u32_e32 v61, vcc, 0, v3, vcc
	v_pk_add_f32 v[46:47], v[46:47], v[78:79]
	v_pk_add_f32 v[64:65], v[6:7], v[102:103]
	v_pk_add_f32 v[66:67], v[4:5], v[100:101]
	v_pk_add_f32 v[68:69], v[8:9], v[106:107]
	v_pk_add_f32 v[70:71], v[38:39], v[104:105]
	v_pk_add_f32 v[72:73], v[40:41], v[110:111]
	v_pk_add_f32 v[76:77], v[44:45], v[114:115]
	v_pk_add_f32 v[78:79], v[48:49], v[118:119]
	v_pk_add_f32 v[80:81], v[50:51], v[116:117]
	v_pk_add_f32 v[84:85], v[52:53], v[122:123]
	v_pk_add_f32 v[86:87], v[54:55], v[120:121]
	v_pk_add_f32 v[88:89], v[56:57], v[126:127]
	v_pk_add_f32 v[90:91], v[58:59], v[124:125]
	v_pk_add_f32 v[94:95], v[62:63], v[128:129]
	global_load_dwordx4 v[2:5], v[60:61], off offset:-4096
	global_load_dwordx4 v[6:9], v[42:43], off offset:1024
	global_load_dwordx4 v[38:41], v[42:43], off offset:2048
	s_nop 0
	global_load_dwordx4 v[42:45], v[42:43], off offset:3072
	s_nop 0
	global_load_dwordx4 v[48:51], v[60:61], off
	global_load_dwordx4 v[52:55], v[60:61], off offset:1024
	global_load_dwordx4 v[56:59], v[60:61], off offset:2048
	s_nop 0
	global_load_dwordx4 v[60:63], v[60:61], off offset:3072
	s_movk_i32 s9, 0x5000
	v_pk_add_f32 v[46:47], v[46:47], v[112:113]
	s_waitcnt vmcnt(7)
	v_pk_add_f32 v[64:65], v[4:5], v[64:65]
	s_waitcnt vmcnt(6)
	v_pk_add_f32 v[96:97], v[8:9], v[68:69]
	v_pk_add_f32 v[98:99], v[6:7], v[70:71]
	v_pk_add_f32 v[66:67], v[2:3], v[66:67]
	s_waitcnt vmcnt(4)
	v_pk_add_f32 v[44:45], v[44:45], v[76:77]
	s_waitcnt vmcnt(2)
	v_pk_add_f32 v[8:9], v[54:55], v[84:85]
	v_lshl_add_u64 v[54:55], v[10:11], 2, s[10:11]
	v_add_co_u32_e32 v6, vcc, s9, v54
	s_waitcnt vmcnt(1)
	v_pk_add_f32 v[2:3], v[58:59], v[88:89]
	v_addc_co_u32_e32 v7, vcc, 0, v55, vcc
	v_pk_add_f32 v[4:5], v[56:57], v[90:91]
	global_load_dwordx4 v[56:59], v[6:7], off offset:-4096
	v_lshl_add_u64 v[76:77], s[12:13], 0, v[12:13]
	v_pk_add_f32 v[72:73], v[40:41], v[72:73]
	v_pk_add_f32 v[46:47], v[42:43], v[46:47]
	v_pk_add_f32 v[40:41], v[50:51], v[78:79]
	v_pk_add_f32 v[42:43], v[48:49], v[80:81]
	global_load_dwordx4 v[48:51], v[76:77], off
	v_mov_b32_e32 v146, 0x1000
	v_mov_b32_e32 v147, 0
	v_lshl_add_u64 v[144:145], v[76:77], 0, v[146:147]
	global_load_dwordx4 v[180:183], v[76:77], off offset:1024
	global_load_dwordx4 v[184:187], v[6:7], off offset:-3072
	global_load_dwordx4 v[188:191], v[76:77], off offset:2048
	global_load_dwordx4 v[192:195], v[6:7], off offset:-2048
	global_load_dwordx4 v[196:199], v[76:77], off offset:3072
	global_load_dwordx4 v[200:203], v[6:7], off offset:-1024
	global_load_dwordx4 v[204:207], v[144:145], off
	global_load_dwordx4 v[208:211], v[6:7], off
	global_load_dwordx4 v[212:215], v[144:145], off offset:1024
	global_load_dwordx4 v[216:219], v[6:7], off offset:1024
	global_load_dwordx4 v[220:223], v[144:145], off offset:2048
	global_load_dwordx4 v[236:239], v[6:7], off offset:2048
	global_load_dwordx4 v[240:243], v[144:145], off offset:3072
	global_load_dwordx4 v[140:143], v[6:7], off offset:3072
	s_mov_b64 s[10:11], 0x4000
	v_pk_add_f32 v[74:75], v[38:39], v[74:75]
	v_pk_add_f32 v[38:39], v[52:53], v[86:87]
	v_lshl_add_u64 v[52:53], v[54:55], 0, s[10:11]
	s_waitcnt vmcnt(2)
	v_pk_add_f32 v[68:69], v[62:63], v[92:93]
	v_pk_add_f32 v[70:71], v[60:61], v[94:95]
	s_mov_b32 s9, 0x9000
	s_waitcnt vmcnt(1)
	v_pk_add_f32 v[58:59], v[58:59], 1.0 op_sel_hi:[1,0]
	v_pk_add_f32 v[56:57], v[56:57], 1.0 op_sel_hi:[1,0]
	v_pk_mul_f32 v[58:59], v[58:59], v[64:65]
	v_pk_mul_f32 v[56:57], v[56:57], v[66:67]
	s_waitcnt vmcnt(0)
	v_pk_fma_f32 v[64:65], v[50:51], s[92:93], v[58:59] op_sel_hi:[1,0,1]
	v_pk_fma_f32 v[66:67], v[48:49], s[92:93], v[56:57] op_sel_hi:[1,0,1]
	v_mov_b64_e32 v[48:49], v[180:181]
	v_mov_b64_e32 v[50:51], v[182:183]
	v_mov_b64_e32 v[56:57], v[184:185]
	v_mov_b64_e32 v[58:59], v[186:187]
	s_waitcnt vmcnt(0)
	v_pk_add_f32 v[58:59], v[58:59], 1.0 op_sel_hi:[1,0]
	v_pk_add_f32 v[56:57], v[56:57], 1.0 op_sel_hi:[1,0]
	v_pk_mul_f32 v[58:59], v[96:97], v[58:59]
	v_pk_mul_f32 v[56:57], v[98:99], v[56:57]
	v_pk_fma_f32 v[60:61], v[50:51], s[92:93], v[58:59] op_sel_hi:[1,0,1]
	v_pk_fma_f32 v[62:63], v[48:49], s[92:93], v[56:57] op_sel_hi:[1,0,1]
	v_mov_b64_e32 v[48:49], v[188:189]
	v_mov_b64_e32 v[50:51], v[190:191]
	v_mov_b64_e32 v[56:57], v[192:193]
	v_mov_b64_e32 v[58:59], v[194:195]
	s_waitcnt vmcnt(0)
	v_pk_add_f32 v[58:59], v[58:59], 1.0 op_sel_hi:[1,0]
	v_pk_add_f32 v[56:57], v[56:57], 1.0 op_sel_hi:[1,0]
	v_pk_mul_f32 v[58:59], v[58:59], v[72:73]
	v_pk_mul_f32 v[56:57], v[56:57], v[74:75]
	v_pk_fma_f32 v[58:59], v[50:51], s[92:93], v[58:59] op_sel_hi:[1,0,1]
	v_pk_fma_f32 v[56:57], v[48:49], s[92:93], v[56:57] op_sel_hi:[1,0,1]
	v_mov_b64_e32 v[48:49], v[196:197]
	v_mov_b64_e32 v[50:51], v[198:199]
	v_mov_b64_e32 v[72:73], v[200:201]
	v_mov_b64_e32 v[74:75], v[202:203]
	v_add_co_u32_e32 v76, vcc, s82, v76
	s_waitcnt vmcnt(0)
	v_pk_add_f32 v[52:53], v[74:75], 1.0 op_sel_hi:[1,0]
	v_pk_add_f32 v[72:73], v[72:73], 1.0 op_sel_hi:[1,0]
	v_pk_mul_f32 v[44:45], v[44:45], v[52:53]
	v_pk_mul_f32 v[46:47], v[46:47], v[72:73]
	v_addc_co_u32_e32 v77, vcc, 0, v77, vcc
	v_pk_fma_f32 v[52:53], v[50:51], s[92:93], v[44:45] op_sel_hi:[1,0,1]
	v_pk_fma_f32 v[50:51], v[48:49], s[92:93], v[46:47] op_sel_hi:[1,0,1]
	v_mov_b64_e32 v[44:45], v[204:205]
	v_mov_b64_e32 v[46:47], v[206:207]
	v_mov_b64_e32 v[72:73], v[208:209]
	v_mov_b64_e32 v[74:75], v[210:211]
	s_waitcnt vmcnt(0)
	v_pk_add_f32 v[48:49], v[74:75], 1.0 op_sel_hi:[1,0]
	v_pk_add_f32 v[72:73], v[72:73], 1.0 op_sel_hi:[1,0]
	v_pk_mul_f32 v[40:41], v[48:49], v[40:41]
	v_pk_mul_f32 v[42:43], v[72:73], v[42:43]
	v_pk_fma_f32 v[48:49], v[46:47], s[92:93], v[40:41] op_sel_hi:[1,0,1]
	v_pk_fma_f32 v[46:47], v[44:45], s[92:93], v[42:43] op_sel_hi:[1,0,1]
	v_mov_b64_e32 v[40:41], v[212:213]
	v_mov_b64_e32 v[42:43], v[214:215]
	v_mov_b64_e32 v[72:73], v[216:217]
	v_mov_b64_e32 v[74:75], v[218:219]
	s_waitcnt vmcnt(0)
	v_pk_add_f32 v[44:45], v[74:75], 1.0 op_sel_hi:[1,0]
	v_pk_add_f32 v[72:73], v[72:73], 1.0 op_sel_hi:[1,0]
	v_pk_mul_f32 v[8:9], v[8:9], v[44:45]
	v_pk_mul_f32 v[38:39], v[38:39], v[72:73]
	v_pk_fma_f32 v[44:45], v[42:43], s[92:93], v[8:9] op_sel_hi:[1,0,1]
	v_pk_fma_f32 v[42:43], v[40:41], s[92:93], v[38:39] op_sel_hi:[1,0,1]
	v_mov_b64_e32 v[38:39], v[220:221]
	v_mov_b64_e32 v[40:41], v[222:223]
	v_mov_b64_e32 v[72:73], v[236:237]
	v_mov_b64_e32 v[74:75], v[238:239]
	s_waitcnt vmcnt(0)
	v_pk_add_f32 v[8:9], v[74:75], 1.0 op_sel_hi:[1,0]
	v_pk_add_f32 v[72:73], v[72:73], 1.0 op_sel_hi:[1,0]
	v_pk_mul_f32 v[2:3], v[8:9], v[2:3]
	v_pk_mul_f32 v[4:5], v[72:73], v[4:5]
	v_pk_fma_f32 v[40:41], v[40:41], s[92:93], v[2:3] op_sel_hi:[1,0,1]
	v_pk_fma_f32 v[38:39], v[38:39], s[92:93], v[4:5] op_sel_hi:[1,0,1]
	v_mov_b64_e32 v[2:3], v[240:241]
	v_mov_b64_e32 v[4:5], v[242:243]
	s_nop 0
	v_mov_b64_e32 v[6:7], v[140:141]
	v_mov_b64_e32 v[8:9], v[142:143]
	s_waitcnt vmcnt(0)
	v_pk_add_f32 v[8:9], v[8:9], 1.0 op_sel_hi:[1,0]
	v_pk_add_f32 v[6:7], v[6:7], 1.0 op_sel_hi:[1,0]
	v_pk_mul_f32 v[8:9], v[68:69], v[8:9]
	v_pk_mul_f32 v[6:7], v[70:71], v[6:7]
	v_pk_fma_f32 v[4:5], v[4:5], s[92:93], v[8:9] op_sel_hi:[1,0,1]
	v_pk_fma_f32 v[2:3], v[2:3], s[92:93], v[6:7] op_sel_hi:[1,0,1]
	v_mov_b32_e32 v6, v66
	v_mov_b32_e32 v7, v62
	v_mov_b32_e32 v8, v67
	v_mov_b32_e32 v9, v63
	v_pk_add_f32 v[6:7], v[6:7], v[8:9]
	v_mov_b32_e32 v8, v64
	v_mov_b32_e32 v9, v60
	v_mov_b32_e32 v68, v65
	v_mov_b32_e32 v69, v61
	v_pk_add_f32 v[8:9], v[8:9], v[68:69]
	v_mov_b32_e32 v68, v56
	v_pk_add_f32 v[6:7], v[6:7], v[8:9]
	v_pk_mov_b32 v[8:9], v[56:57], v[58:59] op_sel:[1,0]
	v_mov_b32_e32 v69, v59
	v_pk_add_f32 v[8:9], v[8:9], v[68:69]
	v_add_f32_e32 v1, 0, v6
	v_pk_add_f32 v[8:9], v[8:9], v[8:9] op_sel:[0,1] op_sel_hi:[1,0]
	v_add_f32_e32 v6, v1, v7
	v_add_f32_e32 v68, v50, v51
	v_add_f32_e32 v70, v52, v53
	v_mov_b32_e32 v7, v46
	v_mov_b32_e32 v9, v47
	v_mov_b32_e32 v69, v48
	v_mov_b32_e32 v71, v49
	v_pk_add_f32 v[6:7], v[6:7], v[8:9]
	v_pk_add_f32 v[8:9], v[68:69], v[70:71]
	v_mov_b32_e32 v68, v42
	v_pk_add_f32 v[6:7], v[6:7], v[8:9]
	v_pk_mov_b32 v[8:9], v[42:43], v[44:45] op_sel:[1,0]
	v_mov_b32_e32 v69, v45
	v_pk_add_f32 v[8:9], v[8:9], v[68:69]
	v_pk_add_f32 v[6:7], v[6:7], v[6:7] op_sel:[0,1] op_sel_hi:[1,0]
	v_pk_add_f32 v[8:9], v[8:9], v[8:9] op_sel:[0,1] op_sel_hi:[1,0]
	v_add_f32_e32 v68, v38, v39
	v_add_f32_e32 v70, v40, v41
	v_mov_b32_e32 v7, v2
	v_mov_b32_e32 v9, v3
	v_mov_b32_e32 v69, v4
	v_mov_b32_e32 v71, v5
	v_pk_add_f32 v[6:7], v[6:7], v[8:9]
	v_pk_add_f32 v[8:9], v[68:69], v[70:71]
	s_nop 0
	v_pk_add_f32 v[6:7], v[6:7], v[8:9]
	s_nop 0
	v_add_f32_e32 v1, v6, v7
	v_and_b32_e32 v6, 64, v249
	v_add_u32_e32 v6, 64, v6
	v_xor_b32_e32 v7, 1, v249
	v_cmp_lt_i32_e32 vcc, v7, v6
	s_nop 1
	v_cndmask_b32_e32 v7, v249, v7, vcc
	v_lshlrev_b32_e32 v72, 2, v7
	ds_bpermute_b32 v7, v72, v1
	s_waitcnt lgkmcnt(0)
	v_add_f32_e32 v1, v1, v7
	v_xor_b32_e32 v7, 2, v249
	v_cmp_lt_i32_e32 vcc, v7, v6
	s_nop 1
	v_cndmask_b32_e32 v7, v249, v7, vcc
	v_lshlrev_b32_e32 v73, 2, v7
	ds_bpermute_b32 v7, v73, v1
	s_waitcnt lgkmcnt(0)
	v_add_f32_e32 v1, v1, v7
	v_xor_b32_e32 v7, 4, v249
	v_cmp_lt_i32_e32 vcc, v7, v6
	s_nop 1
	v_cndmask_b32_e32 v7, v249, v7, vcc
	v_lshlrev_b32_e32 v74, 2, v7
	ds_bpermute_b32 v7, v74, v1
	s_waitcnt lgkmcnt(0)
	v_add_f32_e32 v1, v1, v7
	v_xor_b32_e32 v7, 8, v249
	v_cmp_lt_i32_e32 vcc, v7, v6
	s_nop 1
	v_cndmask_b32_e32 v7, v249, v7, vcc
	v_lshlrev_b32_e32 v75, 2, v7
	ds_bpermute_b32 v7, v75, v1
	s_waitcnt lgkmcnt(0)
	v_add_f32_e32 v1, v1, v7
	v_xor_b32_e32 v7, 16, v249
	v_cmp_lt_i32_e32 vcc, v7, v6
	s_nop 1
	v_cndmask_b32_e32 v7, v249, v7, vcc
	v_lshlrev_b32_e32 v76, 2, v7
	ds_bpermute_b32 v7, v76, v1
	s_waitcnt lgkmcnt(0)
	v_add_f32_e32 v1, v1, v7
	v_xor_b32_e32 v7, 32, v249
	v_cmp_lt_i32_e32 vcc, v7, v6
	s_nop 1
	v_cndmask_b32_e32 v6, v249, v7, vcc
	v_lshlrev_b32_e32 v77, 2, v6
	ds_bpermute_b32 v6, v77, v1
	s_waitcnt lgkmcnt(0)
	v_add_f32_e32 v1, v1, v6
	v_fmamk_f32 v67, v1, 0xba000000, v67
	v_fmamk_f32 v63, v1, 0xba000000, v63
	v_fmamk_f32 v65, v1, 0xba000000, v65
	v_fmac_f32_e32 v66, 0xba000000, v1
	v_fmamk_f32 v61, v1, 0xba000000, v61
	v_fmac_f32_e32 v62, 0xba000000, v1
	v_mov_b32_e32 v8, v67
	v_mov_b32_e32 v9, v63
	v_fmac_f32_e32 v64, 0xba000000, v1
	v_fmac_f32_e32 v60, 0xba000000, v1
	v_mov_b32_e32 v6, v66
	v_mov_b32_e32 v7, v62
	v_pk_mul_f32 v[8:9], v[8:9], v[8:9]
	v_mov_b32_e32 v68, v65
	v_mov_b32_e32 v69, v61
	v_pk_fma_f32 v[6:7], v[6:7], v[6:7], v[8:9]
	v_mov_b32_e32 v8, v64
	v_mov_b32_e32 v9, v60
	v_pk_mul_f32 v[68:69], v[68:69], v[68:69]
	v_fmamk_f32 v57, v1, 0xba000000, v57
	v_pk_fma_f32 v[8:9], v[8:9], v[8:9], v[68:69]
	v_fmac_f32_e32 v56, 0xba000000, v1
	v_pk_add_f32 v[6:7], v[6:7], v[8:9]
	v_fmamk_f32 v59, v1, 0xba000000, v59
	v_fmac_f32_e32 v58, 0xba000000, v1
	v_pk_add_f32 v[6:7], v[6:7], v[6:7] op_sel_hi:[0,1]
	v_pk_mul_f32 v[8:9], v[58:59], v[58:59]
	v_pk_mul_f32 v[68:69], v[56:57], v[56:57]
	v_fmac_f32_e32 v50, 0xba000000, v1
	v_pk_mov_b32 v[70:71], v[68:69], v[8:9] op_sel:[1,0]
	v_mov_b32_e32 v69, v9
	v_fmamk_f32 v51, v1, 0xba000000, v51
	v_fmac_f32_e32 v52, 0xba000000, v1
	v_mul_f32_e32 v6, v50, v50
	v_pk_add_f32 v[8:9], v[70:71], v[68:69]
	v_fmamk_f32 v53, v1, 0xba000000, v53
	v_pk_fma_f32 v[68:69], v[50:51], v[50:51], v[6:7] op_sel_hi:[1,1,0]
	v_mul_f32_e32 v6, v52, v52
	v_pk_add_f32 v[8:9], v[8:9], v[8:9] op_sel_hi:[0,1]
	v_pk_fma_f32 v[70:71], v[52:53], v[52:53], v[6:7] op_sel_hi:[1,1,0]
	v_fmamk_f32 v49, v1, 0xba000000, v49
	v_fmac_f32_e32 v48, 0xba000000, v1
	v_fmamk_f32 v47, v1, 0xba000000, v47
	v_fmac_f32_e32 v46, 0xba000000, v1
	v_mul_f32_e32 v68, v46, v46
	v_mul_f32_e32 v70, v47, v47
	v_mul_f32_e32 v8, v48, v48
	v_mul_f32_e32 v6, v49, v49
	v_pk_add_f32 v[68:69], v[68:69], v[70:71]
	v_pk_add_f32 v[6:7], v[8:9], v[6:7]
	v_fmamk_f32 v43, v1, 0xba000000, v43
	v_pk_add_f32 v[6:7], v[68:69], v[6:7]
	v_fmac_f32_e32 v42, 0xba000000, v1
	v_fmamk_f32 v45, v1, 0xba000000, v45
	v_fmac_f32_e32 v44, 0xba000000, v1
	v_pk_add_f32 v[6:7], v[6:7], v[6:7] op_sel_hi:[0,1]
	v_pk_mul_f32 v[8:9], v[44:45], v[44:45]
	v_pk_mul_f32 v[68:69], v[42:43], v[42:43]
	v_fmac_f32_e32 v38, 0xba000000, v1
	v_pk_mov_b32 v[70:71], v[68:69], v[8:9] op_sel:[1,0]
	v_mov_b32_e32 v69, v9
	v_fmamk_f32 v39, v1, 0xba000000, v39
	v_fmac_f32_e32 v40, 0xba000000, v1
	v_mul_f32_e32 v6, v38, v38
	v_pk_add_f32 v[8:9], v[70:71], v[68:69]
	v_fmamk_f32 v41, v1, 0xba000000, v41
	v_pk_fma_f32 v[68:69], v[38:39], v[38:39], v[6:7] op_sel_hi:[1,1,0]
	v_mul_f32_e32 v6, v40, v40
	v_pk_add_f32 v[8:9], v[8:9], v[8:9] op_sel_hi:[0,1]
	v_pk_fma_f32 v[70:71], v[40:41], v[40:41], v[6:7] op_sel_hi:[1,1,0]
	v_fmamk_f32 v5, v1, 0xba000000, v5
	v_fmac_f32_e32 v4, 0xba000000, v1
	v_fmamk_f32 v3, v1, 0xba000000, v3
	v_fmac_f32_e32 v2, 0xba000000, v1
	v_mul_f32_e32 v68, v2, v2
	v_mul_f32_e32 v70, v3, v3
	v_mul_f32_e32 v8, v4, v4
	v_mul_f32_e32 v6, v5, v5
	v_pk_add_f32 v[68:69], v[68:69], v[70:71]
	v_pk_add_f32 v[6:7], v[8:9], v[6:7]
	s_nop 0
	v_pk_add_f32 v[6:7], v[68:69], v[6:7]
	s_nop 0
	v_add_f32_e32 v1, v6, v7
	ds_bpermute_b32 v6, v72, v1
	s_waitcnt lgkmcnt(0)
	v_add_f32_e32 v1, v1, v6
	ds_bpermute_b32 v6, v73, v1
	s_waitcnt lgkmcnt(0)
	v_add_f32_e32 v1, v1, v6
	ds_bpermute_b32 v6, v74, v1
	s_waitcnt lgkmcnt(0)
	v_add_f32_e32 v1, v1, v6
	ds_bpermute_b32 v6, v75, v1
	s_waitcnt lgkmcnt(0)
	v_add_f32_e32 v1, v1, v6
	ds_bpermute_b32 v6, v76, v1
	s_waitcnt lgkmcnt(0)
	v_add_f32_e32 v1, v1, v6
	ds_bpermute_b32 v6, v77, v1
	s_waitcnt lgkmcnt(0)
	v_add_f32_e32 v1, v1, v6
	v_fmamk_f32 v1, v1, 0x3a000000, v250
	v_cmp_gt_f32_e32 vcc, s96, v1
	v_mul_f32_e32 v6, 0x4f800000, v1
	s_nop 0
	v_cndmask_b32_e32 v1, v1, v6, vcc
	v_sqrt_f32_e32 v6, v1
	s_nop 0
	v_add_u32_e32 v7, -1, v6
	v_fma_f32 v8, -v7, v6, v1
	v_cmp_ge_f32_e64 s[10:11], 0, v8
	v_add_u32_e32 v8, 1, v6
	s_nop 0
	v_cndmask_b32_e64 v7, v6, v7, s[10:11]
	v_fma_f32 v6, -v8, v6, v1
	v_cmp_lt_f32_e64 s[10:11], 0, v6
	s_nop 1
	v_cndmask_b32_e64 v6, v7, v8, s[10:11]
	v_mul_f32_e32 v7, 0x37800000, v6
	v_cndmask_b32_e32 v6, v6, v7, vcc
	v_cmp_class_f32_e32 vcc, v1, v251
	s_nop 1
	v_cndmask_b32_e32 v1, v6, v1, vcc
	v_div_scale_f32 v6, s[10:11], v1, v1, 1.0
	v_rcp_f32_e32 v7, v6
	s_lshl_b64 s[10:11], s[16:17], 13
	v_fma_f32 v8, -v6, v7, 1.0
	v_fmac_f32_e32 v7, v8, v7
	v_div_scale_f32 v8, vcc, 1.0, v1, 1.0
	v_mul_f32_e32 v9, v8, v7
	v_fma_f32 v68, -v6, v9, v8
	v_fmac_f32_e32 v9, v68, v7
	global_load_dwordx4 v[180:183], v[14:15], off
	global_load_dwordx4 v[184:187], v[16:17], off
	s_waitcnt vmcnt(0)
	s_nop 1
	v_mov_b64_e32 v[68:69], v[180:181]
	v_mov_b64_e32 v[70:71], v[182:183]
	s_nop 1
	v_mov_b64_e32 v[72:73], v[184:185]
	v_mov_b64_e32 v[74:75], v[186:187]
	v_fma_f32 v6, -v6, v9, v8
	v_div_fmas_f32 v6, v6, v7, v9
	v_div_fixup_f32 v6, v6, v1, 1.0
	v_pk_mul_f32 v[64:65], v[64:65], v[6:7] op_sel_hi:[1,0]
	v_pk_mul_f32 v[8:9], v[66:67], v[6:7] op_sel_hi:[1,0]
	v_lshl_add_u64 v[66:67], v[34:35], 0, s[10:11]
	s_mov_b64 s[10:11], 0x8000
	v_lshl_add_u64 v[80:81], v[54:55], 0, s[10:11]
	s_mov_b64 s[10:11], 0x6000
	v_lshl_add_u64 v[84:85], v[54:55], 0, s[10:11]
	s_lshl_b64 s[10:11], s[16:17], 12
	s_nop 0
	v_pk_fma_f32 v[70:71], v[70:71], v[64:65], v[74:75]
	v_add_co_u32_e32 v64, vcc, s9, v54
	v_pk_fma_f32 v[68:69], v[68:69], v[8:9], v[72:73]
	s_nop 0
	v_addc_co_u32_e32 v65, vcc, 0, v55, vcc
	s_movk_i32 s9, 0x7000
	global_store_dwordx4 v[66:67], v[68:71], off
	v_add_co_u32_e32 v54, vcc, s9, v54
	global_load_dwordx4 v[180:183], v[64:65], off offset:-4096
	s_waitcnt vmcnt(0)
	s_nop 1
	v_mov_b64_e32 v[72:73], v[180:181]
	v_mov_b64_e32 v[74:75], v[182:183]
	s_nop 0
	v_addc_co_u32_e32 v55, vcc, 0, v55, vcc
	global_load_dwordx4 v[180:183], v[54:55], off offset:-4096
	global_load_dwordx4 v[184:187], v[14:15], off offset:1024
	global_load_dwordx4 v[188:191], v[16:17], off offset:1024
	global_load_dwordx4 v[192:195], v[80:81], off offset:1024
	global_load_dwordx4 v[196:199], v[84:85], off offset:1024
	global_load_dwordx4 v[200:203], v[14:15], off offset:2048
	global_load_dwordx4 v[204:207], v[16:17], off offset:2048
	global_load_dwordx4 v[208:211], v[80:81], off offset:2048
	global_load_dwordx4 v[212:215], v[84:85], off offset:2048
	global_load_dwordx4 v[216:219], v[14:15], off offset:3072
	global_load_dwordx4 v[220:223], v[16:17], off offset:3072
	s_waitcnt vmcnt(0)
	s_nop 1
	v_mov_b64_e32 v[76:77], v[180:181]
	v_mov_b64_e32 v[78:79], v[182:183]
	s_nop 0
	v_pk_add_f32 v[72:73], v[72:73], 1.0 op_sel_hi:[1,0]
	v_pk_add_f32 v[8:9], v[74:75], 1.0 op_sel_hi:[1,0]
	s_nop 0
	v_pk_fma_f32 v[68:69], v[72:73], v[68:69], v[76:77]
	s_nop 0
	s_nop 0
	s_nop 0
	s_nop 0
	v_pk_fma_f32 v[8:9], v[8:9], v[70:71], v[78:79]
	s_nop 0
	s_nop 0
	v_cvt_pk_bf16_f32 v68, v68, v69
	v_bfe_u32 v1, v8, 16, 1
	v_add3_u32 v1, v8, v1, s73
	v_bfe_u32 v7, v9, 16, 1
	v_lshrrev_b32_e32 v1, 16, v1
	v_add3_u32 v7, v9, v7, s73
	v_and_or_b32 v69, v7, s33, v1
	v_lshl_add_u64 v[8:9], v[36:37], 0, s[10:11]
	global_store_dwordx2 v[8:9], v[68:69], off
	s_nop 1
	v_mov_b64_e32 v[68:69], v[184:185]
	v_mov_b64_e32 v[70:71], v[186:187]
	s_nop 0
	s_nop 1
	v_mov_b64_e32 v[72:73], v[188:189]
	v_mov_b64_e32 v[74:75], v[190:191]
	v_pk_mul_f32 v[76:77], v[60:61], v[6:7] op_sel_hi:[1,0]
	v_pk_mul_f32 v[60:61], v[62:63], v[6:7] op_sel_hi:[1,0]
	s_nop 0
	v_pk_fma_f32 v[62:63], v[70:71], v[76:77], v[74:75]
	v_pk_fma_f32 v[60:61], v[68:69], v[60:61], v[72:73]
	global_store_dwordx4 v[66:67], v[60:63], off offset:1024
	s_nop 1
	v_mov_b64_e32 v[68:69], v[192:193]
	v_mov_b64_e32 v[70:71], v[194:195]
	s_nop 1
	v_mov_b64_e32 v[72:73], v[196:197]
	v_mov_b64_e32 v[74:75], v[198:199]
	s_nop 0
	v_pk_add_f32 v[68:69], v[68:69], 1.0 op_sel_hi:[1,0]
	s_nop 0
	v_pk_fma_f32 v[60:61], v[68:69], v[60:61], v[72:73]
	v_pk_add_f32 v[70:71], v[70:71], 1.0 op_sel_hi:[1,0]
	v_pk_fma_f32 v[62:63], v[70:71], v[62:63], v[74:75]
	v_cvt_pk_bf16_f32 v60, v60, v61
	v_bfe_u32 v1, v62, 16, 1
	v_add3_u32 v1, v62, v1, s73
	v_bfe_u32 v7, v63, 16, 1
	v_lshrrev_b32_e32 v1, 16, v1
	v_add3_u32 v7, v63, v7, s73
	v_and_or_b32 v61, v7, s33, v1
	global_store_dwordx2 v[8:9], v[60:61], off offset:512
	s_nop 1
	v_mov_b64_e32 v[60:61], v[200:201]
	v_mov_b64_e32 v[62:63], v[202:203]
	s_nop 0
	s_nop 1
	v_mov_b64_e32 v[68:69], v[204:205]
	v_mov_b64_e32 v[70:71], v[206:207]
	v_pk_mul_f32 v[58:59], v[58:59], v[6:7] op_sel_hi:[1,0]
	v_pk_mul_f32 v[56:57], v[56:57], v[6:7] op_sel_hi:[1,0]
	s_nop 0
	v_pk_fma_f32 v[58:59], v[62:63], v[58:59], v[70:71]
	v_pk_fma_f32 v[56:57], v[60:61], v[56:57], v[68:69]
	global_store_dwordx4 v[66:67], v[56:59], off offset:2048
	s_nop 1
	v_mov_b64_e32 v[60:61], v[208:209]
	v_mov_b64_e32 v[62:63], v[210:211]
	s_nop 1
	v_mov_b64_e32 v[68:69], v[212:213]
	v_mov_b64_e32 v[70:71], v[214:215]
	s_nop 0
	v_pk_add_f32 v[60:61], v[60:61], 1.0 op_sel_hi:[1,0]
	s_nop 0
	v_pk_fma_f32 v[56:57], v[56:57], v[60:61], v[68:69]
	v_pk_add_f32 v[62:63], v[62:63], 1.0 op_sel_hi:[1,0]
	v_pk_fma_f32 v[58:59], v[58:59], v[62:63], v[70:71]
	v_cvt_pk_bf16_f32 v56, v56, v57
	v_bfe_u32 v1, v58, 16, 1
	v_add3_u32 v1, v58, v1, s73
	v_bfe_u32 v7, v59, 16, 1
	v_lshrrev_b32_e32 v1, 16, v1
	v_add3_u32 v7, v59, v7, s73
	v_and_or_b32 v57, v7, s33, v1
	global_store_dwordx2 v[8:9], v[56:57], off offset:1024
	s_nop 1
	v_mov_b64_e32 v[56:57], v[216:217]
	v_mov_b64_e32 v[58:59], v[218:219]
	s_nop 0
	s_nop 1
	v_mov_b64_e32 v[60:61], v[220:221]
	v_mov_b64_e32 v[62:63], v[222:223]
	v_pk_mul_f32 v[52:53], v[52:53], v[6:7] op_sel_hi:[1,0]
	v_pk_mul_f32 v[50:51], v[50:51], v[6:7] op_sel_hi:[1,0]
	s_nop 0
	v_pk_fma_f32 v[52:53], v[52:53], v[58:59], v[62:63]
	v_pk_fma_f32 v[50:51], v[50:51], v[56:57], v[60:61]
	global_store_dwordx4 v[66:67], v[50:53], off offset:3072
	global_load_dwordx4 v[180:183], v[80:81], off offset:3072
	global_load_dwordx4 v[184:187], v[84:85], off offset:3072
	global_load_dwordx4 v[188:191], v[18:19], off
	global_load_dwordx4 v[192:195], v[20:21], off
	global_load_dwordx4 v[196:199], v[64:65], off
	global_load_dwordx4 v[200:203], v[54:55], off
	global_load_dwordx4 v[204:207], v[22:23], off
	global_load_dwordx4 v[208:211], v[24:25], off
	global_load_dwordx4 v[212:215], v[64:65], off offset:1024
	global_load_dwordx4 v[216:219], v[54:55], off offset:1024
	global_load_dwordx4 v[220:223], v[26:27], off
	s_waitcnt vmcnt(0)
	s_nop 1
	v_mov_b64_e32 v[56:57], v[180:181]
	v_mov_b64_e32 v[58:59], v[182:183]
	s_nop 1
	v_mov_b64_e32 v[60:61], v[184:185]
	v_mov_b64_e32 v[62:63], v[186:187]
	s_nop 0
	v_pk_add_f32 v[56:57], v[56:57], 1.0 op_sel_hi:[1,0]
	s_nop 0
	v_pk_fma_f32 v[50:51], v[50:51], v[56:57], v[60:61]
	v_pk_add_f32 v[58:59], v[58:59], 1.0 op_sel_hi:[1,0]
	v_pk_fma_f32 v[52:53], v[52:53], v[58:59], v[62:63]
	v_cvt_pk_bf16_f32 v50, v50, v51
	v_bfe_u32 v1, v52, 16, 1
	v_add3_u32 v1, v52, v1, s73
	v_bfe_u32 v7, v53, 16, 1
	v_lshrrev_b32_e32 v1, 16, v1
	v_add3_u32 v7, v53, v7, s73
	v_and_or_b32 v51, v7, s33, v1
	global_store_dwordx2 v[8:9], v[50:51], off offset:1536
	s_nop 1
	v_mov_b64_e32 v[50:51], v[188:189]
	v_mov_b64_e32 v[52:53], v[190:191]
	s_nop 0
	s_nop 1
	v_mov_b64_e32 v[56:57], v[192:193]
	v_mov_b64_e32 v[58:59], v[194:195]
	v_pk_mul_f32 v[46:47], v[46:47], v[6:7] op_sel_hi:[1,0]
	v_pk_mul_f32 v[60:61], v[48:49], v[6:7] op_sel_hi:[1,0]
	s_nop 0
	v_pk_fma_f32 v[48:49], v[46:47], v[50:51], v[56:57]
	v_add_co_u32_e32 v46, vcc, s82, v66
	v_pk_fma_f32 v[50:51], v[60:61], v[52:53], v[58:59]
	s_nop 0
	v_addc_co_u32_e32 v47, vcc, 0, v67, vcc
	global_store_dwordx4 v[46:47], v[48:51], off
	s_nop 1
	v_mov_b64_e32 v[56:57], v[196:197]
	v_mov_b64_e32 v[58:59], v[198:199]
	s_nop 1
	v_mov_b64_e32 v[60:61], v[200:201]
	v_mov_b64_e32 v[62:63], v[202:203]
	s_nop 0
	v_pk_add_f32 v[56:57], v[56:57], 1.0 op_sel_hi:[1,0]
	s_nop 0
	v_pk_fma_f32 v[48:49], v[48:49], v[56:57], v[60:61]
	v_pk_add_f32 v[52:53], v[58:59], 1.0 op_sel_hi:[1,0]
	v_pk_fma_f32 v[50:51], v[50:51], v[52:53], v[62:63]
	v_cvt_pk_bf16_f32 v48, v48, v49
	v_bfe_u32 v1, v50, 16, 1
	v_add3_u32 v1, v50, v1, s73
	v_bfe_u32 v7, v51, 16, 1
	v_lshrrev_b32_e32 v1, 16, v1
	v_add3_u32 v7, v51, v7, s73
	v_and_or_b32 v49, v7, s33, v1
	global_store_dwordx2 v[8:9], v[48:49], off offset:2048
	s_nop 1
	v_mov_b64_e32 v[48:49], v[204:205]
	v_mov_b64_e32 v[50:51], v[206:207]
	s_nop 0
	s_nop 1
	v_mov_b64_e32 v[56:57], v[208:209]
	v_mov_b64_e32 v[58:59], v[210:211]
	v_pk_mul_f32 v[44:45], v[44:45], v[6:7] op_sel_hi:[1,0]
	v_pk_mul_f32 v[42:43], v[42:43], v[6:7] op_sel_hi:[1,0]
	s_nop 0
	v_pk_fma_f32 v[44:45], v[44:45], v[50:51], v[58:59]
	v_pk_fma_f32 v[42:43], v[42:43], v[48:49], v[56:57]
	global_store_dwordx4 v[46:47], v[42:45], off offset:1024
	s_nop 1
	v_mov_b64_e32 v[48:49], v[212:213]
	v_mov_b64_e32 v[50:51], v[214:215]
	s_nop 1
	v_mov_b64_e32 v[56:57], v[216:217]
	v_mov_b64_e32 v[58:59], v[218:219]
	s_nop 0
	v_pk_add_f32 v[48:49], v[48:49], 1.0 op_sel_hi:[1,0]
	s_nop 0
	v_pk_fma_f32 v[42:43], v[42:43], v[48:49], v[56:57]
	v_pk_add_f32 v[50:51], v[50:51], 1.0 op_sel_hi:[1,0]
	v_pk_fma_f32 v[44:45], v[44:45], v[50:51], v[58:59]
	v_cvt_pk_bf16_f32 v42, v42, v43
	v_bfe_u32 v1, v44, 16, 1
	v_add3_u32 v1, v44, v1, s73
	v_bfe_u32 v7, v45, 16, 1
	v_lshrrev_b32_e32 v1, 16, v1
	v_add3_u32 v7, v45, v7, s73
	v_and_or_b32 v43, v7, s33, v1
	global_store_dwordx2 v[8:9], v[42:43], off offset:2560
	s_nop 1
	v_mov_b64_e32 v[42:43], v[220:221]
	v_mov_b64_e32 v[44:45], v[222:223]
	s_nop 0
	global_load_dwordx4 v[180:183], v[28:29], off
	global_load_dwordx4 v[184:187], v[64:65], off offset:2048
	global_load_dwordx4 v[188:191], v[54:55], off offset:2048
	global_load_dwordx4 v[192:195], v[30:31], off
	global_load_dwordx4 v[196:199], v[32:33], off
	global_load_dwordx4 v[200:203], v[64:65], off offset:3072
	global_load_dwordx4 v[204:207], v[54:55], off offset:3072
	s_waitcnt vmcnt(0)
	s_nop 1
	v_mov_b64_e32 v[48:49], v[180:181]
	v_mov_b64_e32 v[50:51], v[182:183]
	v_pk_mul_f32 v[40:41], v[40:41], v[6:7] op_sel_hi:[1,0]
	v_pk_mul_f32 v[38:39], v[38:39], v[6:7] op_sel_hi:[1,0]
	s_nop 0
	v_pk_fma_f32 v[40:41], v[40:41], v[44:45], v[50:51]
	v_pk_fma_f32 v[38:39], v[38:39], v[42:43], v[48:49]
	global_store_dwordx4 v[46:47], v[38:41], off offset:2048
	s_nop 1
	v_mov_b64_e32 v[42:43], v[184:185]
	v_mov_b64_e32 v[44:45], v[186:187]
	s_nop 1
	v_mov_b64_e32 v[48:49], v[188:189]
	v_mov_b64_e32 v[50:51], v[190:191]
	s_nop 0
	v_pk_add_f32 v[42:43], v[42:43], 1.0 op_sel_hi:[1,0]
	s_nop 0
	v_pk_fma_f32 v[38:39], v[38:39], v[42:43], v[48:49]
	v_pk_add_f32 v[44:45], v[44:45], 1.0 op_sel_hi:[1,0]
	v_pk_fma_f32 v[40:41], v[40:41], v[44:45], v[50:51]
	v_cvt_pk_bf16_f32 v38, v38, v39
	v_bfe_u32 v1, v40, 16, 1
	v_add3_u32 v1, v40, v1, s73
	v_bfe_u32 v7, v41, 16, 1
	v_lshrrev_b32_e32 v1, 16, v1
	v_add3_u32 v7, v41, v7, s73
	v_and_or_b32 v39, v7, s33, v1
	global_store_dwordx2 v[8:9], v[38:39], off offset:3072
	s_nop 1
	v_mov_b64_e32 v[38:39], v[192:193]
	v_mov_b64_e32 v[40:41], v[194:195]
	s_nop 0
	s_nop 1
	v_mov_b64_e32 v[42:43], v[196:197]
	v_mov_b64_e32 v[44:45], v[198:199]
	v_pk_mul_f32 v[4:5], v[4:5], v[6:7] op_sel_hi:[1,0]
	v_pk_mul_f32 v[2:3], v[2:3], v[6:7] op_sel_hi:[1,0]
	s_nop 0
	v_pk_fma_f32 v[4:5], v[4:5], v[40:41], v[44:45]
	v_pk_fma_f32 v[2:3], v[2:3], v[38:39], v[42:43]
	global_store_dwordx4 v[46:47], v[2:5], off offset:3072
	s_nop 1
	v_mov_b64_e32 v[38:39], v[200:201]
	v_mov_b64_e32 v[40:41], v[202:203]
	s_nop 1
	v_mov_b64_e32 v[42:43], v[204:205]
	v_mov_b64_e32 v[44:45], v[206:207]
	s_nop 0
	v_pk_add_f32 v[38:39], v[38:39], 1.0 op_sel_hi:[1,0]
	s_nop 0
	v_pk_fma_f32 v[2:3], v[2:3], v[38:39], v[42:43]
	v_pk_add_f32 v[6:7], v[40:41], 1.0 op_sel_hi:[1,0]
	v_pk_fma_f32 v[4:5], v[4:5], v[6:7], v[44:45]
	v_cvt_pk_bf16_f32 v2, v2, v3
	v_bfe_u32 v1, v4, 16, 1
	v_add3_u32 v1, v4, v1, s73
	v_bfe_u32 v3, v5, 16, 1
	v_lshrrev_b32_e32 v1, 16, v1
	v_add3_u32 v3, v5, v3, s73
	v_and_or_b32 v3, v3, s33, v1
	global_store_dwordx2 v[8:9], v[2:3], off offset:3584
	s_branch .LBB0_1221

.LBB0_1757:
	s_abs_i32 s9, s28
	v_readlane_b32 s12, v253, 56
	s_mul_hi_u32 s12, s9, s12
	v_readlane_b32 s15, v253, 57
	s_mul_i32 s13, s12, s15
	s_ashr_i32 s8, s28, 31
	s_sub_i32 s9, s9, s13
	s_xor_b32 s8, s8, s43
	s_add_i32 s13, s12, 1
	s_sub_i32 s14, s9, s15
	s_cmp_ge_u32 s9, s15
	s_cselect_b32 s12, s13, s12
	s_cselect_b32 s9, s14, s9
	s_add_i32 s13, s12, 1
	s_cmp_ge_u32 s9, s15
	s_cselect_b32 s9, s13, s12
	s_xor_b32 s9, s9, s8
	s_sub_i32 s8, s9, s8
	s_add_i32 s8, s28, s8
	s_and_b32 s8, s8, 7
	v_readlane_b32 s9, v253, 15
	s_cmp_lg_u32 s9, s8
	s_cbranch_scc1 .LBB0_1756
	s_add_i32 s14, s28, 0x2000
	v_mov_b32_e32 v1, v232
	s_mov_b64 s[12:13], s[46:47]
	s_mov_b64 s[8:9], s[0:1]
	v_mov_b32_e32 v2, v0
	s_mov_b64 s[16:17], s[44:45]
	s_add_u32 s15, s12, 0x25d1e000
	v_readlane_b32 s34, v254, 40
	s_addc_u32 s20, s13, 0
	v_readlane_b32 s35, v254, 41
	s_and_b64 s[18:19], s[34:35], exec
	s_cselect_b32 s27, s20, s17
	s_cselect_b32 s30, s15, s16
	s_add_u32 s15, s12, 0xcc1b000
	s_addc_u32 s18, s13, 0
	s_and_b64 s[16:17], s[34:35], exec
	s_cselect_b32 s26, s18, 0
	s_cselect_b32 s29, s15, 0
	s_add_u32 s16, s12, 0x100000
	s_addc_u32 s17, s13, 0
	s_lshr_b32 s15, s28, 3
	s_add_i32 s15, s15, 1
	s_cmp_gt_i32 s28, -1
	v_lshlrev_b32_e32 v40, 2, v1
	s_cselect_b32 s15, s15, 0
	v_ashrrev_i32_e32 v41, 31, v40
	s_add_i32 s18, s15, 33
	s_waitcnt lgkmcnt(0)
	v_mov_b64_e32 v[2:3], s[16:17]
	v_mov_b32_e32 v4, 0xc000
	s_add_i32 s15, s15, s97
	v_lshlrev_b64 v[42:43], 2, v[40:41]
	v_mad_u64_u32 v[38:39], s[16:17], s18, v4, v[2:3]
	v_mad_u64_u32 v[2:3], s[16:17], s15, v4, v[2:3]
	v_lshl_add_u64 v[4:5], s[12:13], 0, v[42:43]
	v_lshl_add_u64 v[4:5], v[4:5], 0, s[10:11]
	s_mov_b32 s22, 0xfebff000
	v_add_co_u32_e32 v14, vcc, s22, v4
	s_mov_b32 s22, 0xfec00000
	s_nop 0
	v_addc_co_u32_e32 v15, vcc, -1, v5, vcc
	v_add_co_u32_e32 v34, vcc, s22, v4
	s_mov_b32 s22, 0xfedff000
	s_nop 0
	v_addc_co_u32_e32 v35, vcc, -1, v5, vcc
	v_add_co_u32_e32 v52, vcc, s22, v4
	s_mov_b32 s22, 0xfee00000
	s_nop 0
	v_addc_co_u32_e32 v53, vcc, -1, v5, vcc
	v_add_co_u32_e32 v72, vcc, s22, v4
	s_mov_b32 s22, 0xfefff000
	s_nop 0
	v_addc_co_u32_e32 v73, vcc, -1, v5, vcc
	v_add_co_u32_e32 v80, vcc, s22, v4
	global_load_dwordx4 v[6:9], v[14:15], off offset:-3072
	global_load_dwordx4 v[10:13], v[14:15], off offset:-2048
	s_nop 0
	global_load_dwordx4 v[14:17], v[14:15], off offset:-1024
	s_nop 0
	global_load_dwordx4 v[18:21], v[34:35], off offset:-4096
	global_load_dwordx4 v[22:25], v[34:35], off offset:-3072
	global_load_dwordx4 v[26:29], v[34:35], off offset:-2048
	global_load_dwordx4 v[30:33], v[34:35], off offset:-1024
	s_nop 0
	global_load_dwordx4 v[34:37], v[34:35], off
	s_nop 0
	global_load_dwordx4 v[44:47], v[52:53], off offset:-3072
	global_load_dwordx4 v[48:51], v[52:53], off offset:-2048
	s_nop 0
	global_load_dwordx4 v[52:55], v[52:53], off offset:-1024
	v_addc_co_u32_e32 v81, vcc, -1, v5, vcc
	s_mov_b32 s22, 0xff000000
	global_load_dwordx4 v[56:59], v[72:73], off offset:-4096
	global_load_dwordx4 v[60:63], v[72:73], off offset:-3072
	global_load_dwordx4 v[64:67], v[72:73], off offset:-2048
	global_load_dwordx4 v[68:71], v[72:73], off offset:-1024
	s_nop 0
	global_load_dwordx4 v[72:75], v[72:73], off
	s_nop 0
	global_load_dwordx4 v[76:79], v[80:81], off offset:-3072
	global_load_dwordx4 v[84:87], v[80:81], off offset:-2048
	global_load_dwordx4 v[88:91], v[80:81], off offset:-1024
	v_add_co_u32_e32 v80, vcc, s22, v4
	s_mov_b32 s22, 0xff1ff000
	s_nop 0
	v_addc_co_u32_e32 v81, vcc, -1, v5, vcc
	global_load_dwordx4 v[92:95], v[80:81], off offset:-4096
	global_load_dwordx4 v[96:99], v[80:81], off offset:-3072
	global_load_dwordx4 v[100:103], v[80:81], off offset:-2048
	global_load_dwordx4 v[104:107], v[80:81], off offset:-1024
	global_load_dwordx4 v[108:111], v[80:81], off
	s_ashr_i32 s15, s14, 31
	s_lshl_b64 s[16:17], s[14:15], 11
	s_lshl_b64 s[18:19], s[14:15], 13
	s_add_u32 s20, s12, s18
	s_addc_u32 s21, s13, s19
	v_lshl_add_u64 v[2:3], v[2:3], 0, v[42:43]
	s_waitcnt vmcnt(15)
	v_pk_add_f32 v[8:9], v[8:9], v[46:47]
	v_pk_add_f32 v[6:7], v[6:7], v[44:45]
	s_waitcnt vmcnt(13)
	v_pk_add_f32 v[14:15], v[14:15], v[52:53]
	v_pk_add_f32 v[12:13], v[12:13], v[50:51]
	v_pk_add_f32 v[10:11], v[10:11], v[48:49]
	v_pk_add_f32 v[16:17], v[16:17], v[54:55]
	s_waitcnt vmcnt(8)
	v_pk_add_f32 v[34:35], v[34:35], v[72:73]
	s_waitcnt vmcnt(5)
	v_pk_add_f32 v[88:89], v[14:15], v[88:89]
	v_add_co_u32_e32 v14, vcc, s22, v4
	s_mov_b32 s22, 0xff200000
	s_nop 0
	v_addc_co_u32_e32 v15, vcc, -1, v5, vcc
	s_waitcnt vmcnt(0)
	v_pk_add_f32 v[108:109], v[34:35], v[108:109]
	v_add_co_u32_e32 v34, vcc, s22, v4
	s_mov_b32 s22, 0xff3ff000
	s_nop 0
	v_addc_co_u32_e32 v35, vcc, -1, v5, vcc
	v_add_co_u32_e32 v52, vcc, s22, v4
	v_pk_add_f32 v[20:21], v[20:21], v[58:59]
	v_pk_add_f32 v[18:19], v[18:19], v[56:57]
	v_pk_add_f32 v[24:25], v[24:25], v[62:63]
	v_pk_add_f32 v[22:23], v[22:23], v[60:61]
	v_pk_add_f32 v[28:29], v[28:29], v[66:67]
	v_pk_add_f32 v[26:27], v[26:27], v[64:65]
	v_pk_add_f32 v[32:33], v[32:33], v[70:71]
	v_pk_add_f32 v[30:31], v[30:31], v[68:69]
	v_pk_add_f32 v[36:37], v[36:37], v[74:75]
	v_pk_add_f32 v[78:79], v[8:9], v[78:79]
	v_pk_add_f32 v[76:77], v[6:7], v[76:77]
	v_pk_add_f32 v[80:81], v[12:13], v[86:87]
	v_pk_add_f32 v[84:85], v[10:11], v[84:85]
	v_pk_add_f32 v[86:87], v[16:17], v[90:91]
	global_load_dwordx4 v[6:9], v[14:15], off offset:-3072
	global_load_dwordx4 v[10:13], v[14:15], off offset:-2048
	s_nop 0
	global_load_dwordx4 v[14:17], v[14:15], off offset:-1024
	v_addc_co_u32_e32 v53, vcc, -1, v5, vcc
	s_mov_b32 s22, 0xff400000
	v_pk_add_f32 v[90:91], v[20:21], v[94:95]
	v_pk_add_f32 v[92:93], v[18:19], v[92:93]
	v_pk_add_f32 v[94:95], v[24:25], v[98:99]
	v_pk_add_f32 v[96:97], v[22:23], v[96:97]
	v_pk_add_f32 v[98:99], v[28:29], v[102:103]
	v_pk_add_f32 v[100:101], v[26:27], v[100:101]
	v_pk_add_f32 v[102:103], v[32:33], v[106:107]
	v_pk_add_f32 v[104:105], v[30:31], v[104:105]
	v_pk_add_f32 v[106:107], v[36:37], v[110:111]
	global_load_dwordx4 v[18:21], v[34:35], off offset:-4096
	global_load_dwordx4 v[22:25], v[34:35], off offset:-3072
	global_load_dwordx4 v[26:29], v[34:35], off offset:-2048
	global_load_dwordx4 v[30:33], v[34:35], off offset:-1024
	s_nop 0
	global_load_dwordx4 v[34:37], v[34:35], off
	s_nop 0
	global_load_dwordx4 v[44:47], v[52:53], off offset:-3072
	global_load_dwordx4 v[48:51], v[52:53], off offset:-2048
	s_nop 0
	global_load_dwordx4 v[52:55], v[52:53], off offset:-1024
	v_add_co_u32_e32 v72, vcc, s22, v4
	s_mov_b32 s22, 0xff5ff000
	s_nop 0
	v_addc_co_u32_e32 v73, vcc, -1, v5, vcc
	global_load_dwordx4 v[56:59], v[72:73], off offset:-4096
	global_load_dwordx4 v[60:63], v[72:73], off offset:-3072
	global_load_dwordx4 v[64:67], v[72:73], off offset:-2048
	global_load_dwordx4 v[68:71], v[72:73], off offset:-1024
	s_nop 0
	global_load_dwordx4 v[72:75], v[72:73], off
	s_waitcnt vmcnt(15)
	v_pk_add_f32 v[8:9], v[78:79], v[8:9]
	s_waitcnt vmcnt(14)
	v_pk_add_f32 v[12:13], v[80:81], v[12:13]
	s_waitcnt vmcnt(13)
	v_pk_add_f32 v[16:17], v[86:87], v[16:17]
	v_pk_add_f32 v[80:81], v[88:89], v[14:15]
	v_pk_add_f32 v[78:79], v[84:85], v[10:11]
	v_pk_add_f32 v[76:77], v[76:77], v[6:7]
	s_waitcnt vmcnt(12)
	v_pk_add_f32 v[84:85], v[92:93], v[18:19]
	v_pk_add_f32 v[20:21], v[90:91], v[20:21]
	s_waitcnt vmcnt(11)
	v_pk_add_f32 v[24:25], v[94:95], v[24:25]
	s_waitcnt vmcnt(7)
	v_pk_add_f32 v[6:7], v[8:9], v[46:47]
	v_pk_add_f32 v[36:37], v[106:107], v[36:37]
	s_waitcnt vmcnt(5)
	v_pk_add_f32 v[14:15], v[16:17], v[54:55]
	v_pk_add_f32 v[16:17], v[80:81], v[52:53]
	v_add_co_u32_e32 v52, vcc, s22, v4
	v_pk_add_f32 v[92:93], v[108:109], v[34:35]
	s_nop 0
	v_addc_co_u32_e32 v53, vcc, -1, v5, vcc
	s_mov_b32 s22, 0xff600000
	s_waitcnt vmcnt(0)
	v_pk_add_f32 v[34:35], v[36:37], v[74:75]
	v_pk_add_f32 v[36:37], v[92:93], v[72:73]
	v_add_co_u32_e32 v72, vcc, s22, v4
	v_pk_add_f32 v[8:9], v[76:77], v[44:45]
	v_pk_add_f32 v[10:11], v[12:13], v[50:51]
	v_pk_add_f32 v[12:13], v[78:79], v[48:49]
	global_load_dwordx4 v[44:47], v[52:53], off offset:-3072
	global_load_dwordx4 v[48:51], v[52:53], off offset:-2048
	s_nop 0
	global_load_dwordx4 v[52:55], v[52:53], off offset:-1024
	v_addc_co_u32_e32 v73, vcc, -1, v5, vcc
	s_mov_b32 s22, 0xff7ff000
	v_pk_add_f32 v[86:87], v[96:97], v[22:23]
	v_pk_add_f32 v[28:29], v[98:99], v[28:29]
	v_pk_add_f32 v[88:89], v[100:101], v[26:27]
	v_pk_add_f32 v[32:33], v[102:103], v[32:33]
	v_pk_add_f32 v[90:91], v[104:105], v[30:31]
	v_add_co_u32_e32 v80, vcc, s22, v4
	v_pk_add_f32 v[18:19], v[20:21], v[58:59]
	v_pk_add_f32 v[20:21], v[84:85], v[56:57]
	v_pk_add_f32 v[22:23], v[24:25], v[62:63]
	v_pk_add_f32 v[24:25], v[86:87], v[60:61]
	v_pk_add_f32 v[26:27], v[28:29], v[66:67]
	v_pk_add_f32 v[28:29], v[88:89], v[64:65]
	v_pk_add_f32 v[30:31], v[32:33], v[70:71]
	v_pk_add_f32 v[32:33], v[90:91], v[68:69]
	global_load_dwordx4 v[56:59], v[72:73], off offset:-4096
	global_load_dwordx4 v[60:63], v[72:73], off offset:-3072
	global_load_dwordx4 v[64:67], v[72:73], off offset:-2048
	global_load_dwordx4 v[68:71], v[72:73], off offset:-1024
	s_nop 0
	global_load_dwordx4 v[72:75], v[72:73], off
	v_addc_co_u32_e32 v81, vcc, -1, v5, vcc
	s_mov_b32 s22, 0xff800000
	global_load_dwordx4 v[76:79], v[80:81], off offset:-3072
	global_load_dwordx4 v[84:87], v[80:81], off offset:-2048
	global_load_dwordx4 v[88:91], v[80:81], off offset:-1024
	v_add_co_u32_e32 v80, vcc, s22, v4
	s_mov_b32 s22, 0xff9ff000
	s_nop 0
	v_addc_co_u32_e32 v81, vcc, -1, v5, vcc
	global_load_dwordx4 v[92:95], v[80:81], off offset:-4096
	global_load_dwordx4 v[96:99], v[80:81], off offset:-3072
	global_load_dwordx4 v[100:103], v[80:81], off offset:-2048
	global_load_dwordx4 v[104:107], v[80:81], off offset:-1024
	global_load_dwordx4 v[108:111], v[80:81], off
	s_waitcnt vmcnt(15)
	v_pk_add_f32 v[6:7], v[6:7], v[46:47]
	v_pk_add_f32 v[8:9], v[8:9], v[44:45]
	s_waitcnt vmcnt(13)
	v_pk_add_f32 v[16:17], v[16:17], v[52:53]
	v_add_co_u32_e32 v52, vcc, s22, v4
	s_mov_b32 s22, 0xffa00000
	s_nop 0
	v_addc_co_u32_e32 v53, vcc, -1, v5, vcc
	v_pk_add_f32 v[10:11], v[10:11], v[50:51]
	v_pk_add_f32 v[12:13], v[12:13], v[48:49]
	v_pk_add_f32 v[14:15], v[14:15], v[54:55]
	s_waitcnt vmcnt(12)
	v_pk_add_f32 v[18:19], v[18:19], v[58:59]
	v_pk_add_f32 v[20:21], v[20:21], v[56:57]
	s_waitcnt vmcnt(11)
	v_pk_add_f32 v[22:23], v[22:23], v[62:63]
	v_pk_add_f32 v[24:25], v[24:25], v[60:61]
	s_waitcnt vmcnt(8)
	v_pk_add_f32 v[46:47], v[36:37], v[72:73]
	v_add_co_u32_e32 v72, vcc, s22, v4
	s_mov_b32 s22, 0xffbff000
	s_nop 0
	v_addc_co_u32_e32 v73, vcc, -1, v5, vcc
	v_pk_add_f32 v[26:27], v[26:27], v[66:67]
	v_pk_add_f32 v[28:29], v[28:29], v[64:65]
	v_pk_add_f32 v[30:31], v[30:31], v[70:71]
	v_pk_add_f32 v[32:33], v[32:33], v[68:69]
	v_pk_add_f32 v[44:45], v[34:35], v[74:75]
	v_add_co_u32_e32 v80, vcc, s22, v4
	s_waitcnt vmcnt(7)
	v_pk_add_f32 v[34:35], v[6:7], v[78:79]
	v_pk_add_f32 v[36:37], v[8:9], v[76:77]
	s_waitcnt vmcnt(6)
	v_pk_add_f32 v[6:7], v[10:11], v[86:87]
	v_pk_add_f32 v[8:9], v[12:13], v[84:85]
	s_waitcnt vmcnt(5)
	v_pk_add_f32 v[10:11], v[14:15], v[90:91]
	v_pk_add_f32 v[12:13], v[16:17], v[88:89]
	s_waitcnt vmcnt(4)
	v_pk_add_f32 v[14:15], v[18:19], v[94:95]
	v_pk_add_f32 v[16:17], v[20:21], v[92:93]
	s_waitcnt vmcnt(3)
	v_pk_add_f32 v[18:19], v[22:23], v[98:99]
	v_pk_add_f32 v[20:21], v[24:25], v[96:97]
	s_waitcnt vmcnt(2)
	v_pk_add_f32 v[22:23], v[26:27], v[102:103]
	v_pk_add_f32 v[24:25], v[28:29], v[100:101]
	s_waitcnt vmcnt(1)
	v_pk_add_f32 v[26:27], v[30:31], v[106:107]
	v_pk_add_f32 v[28:29], v[32:33], v[104:105]
	s_waitcnt vmcnt(0)
	v_pk_add_f32 v[30:31], v[44:45], v[110:111]
	v_pk_add_f32 v[32:33], v[46:47], v[108:109]
	global_load_dwordx4 v[44:47], v[52:53], off offset:-3072
	global_load_dwordx4 v[48:51], v[52:53], off offset:-2048
	s_nop 0
	global_load_dwordx4 v[52:55], v[52:53], off offset:-1024
	v_addc_co_u32_e32 v81, vcc, -1, v5, vcc
	global_load_dwordx4 v[56:59], v[72:73], off offset:-4096
	global_load_dwordx4 v[60:63], v[72:73], off offset:-3072
	global_load_dwordx4 v[64:67], v[72:73], off offset:-2048
	global_load_dwordx4 v[68:71], v[72:73], off offset:-1024
	s_nop 0
	global_load_dwordx4 v[72:75], v[72:73], off
	s_nop 0
	global_load_dwordx4 v[76:79], v[80:81], off offset:-3072
	global_load_dwordx4 v[84:87], v[80:81], off offset:-2048
	global_load_dwordx4 v[88:91], v[80:81], off offset:-1024
	s_mov_b32 s22, 0xffc00000
	v_add_co_u32_e32 v80, vcc, s22, v4
	s_mov_b32 s22, 0xffdff000
	s_nop 0
	v_addc_co_u32_e32 v81, vcc, -1, v5, vcc
	global_load_dwordx4 v[92:95], v[80:81], off offset:-4096
	global_load_dwordx4 v[96:99], v[80:81], off offset:-3072
	global_load_dwordx4 v[100:103], v[80:81], off offset:-2048
	global_load_dwordx4 v[104:107], v[80:81], off offset:-1024
	global_load_dwordx4 v[108:111], v[80:81], off
	s_waitcnt vmcnt(15)
	v_pk_add_f32 v[34:35], v[34:35], v[46:47]
	s_waitcnt vmcnt(14)
	v_pk_add_f32 v[6:7], v[6:7], v[50:51]
	s_waitcnt vmcnt(13)
	v_pk_add_f32 v[10:11], v[10:11], v[54:55]
	s_waitcnt vmcnt(12)
	v_pk_add_f32 v[14:15], v[14:15], v[58:59]
	s_waitcnt vmcnt(7)
	v_pk_add_f32 v[78:79], v[34:35], v[78:79]
	s_waitcnt vmcnt(6)
	v_pk_add_f32 v[80:81], v[6:7], v[86:87]
	s_waitcnt vmcnt(5)
	v_pk_add_f32 v[86:87], v[10:11], v[90:91]
	v_pk_add_f32 v[36:37], v[36:37], v[44:45]
	v_pk_add_f32 v[8:9], v[8:9], v[48:49]
	s_waitcnt vmcnt(4)
	v_pk_add_f32 v[90:91], v[14:15], v[94:95]
	v_add_co_u32_e32 v14, vcc, s22, v4
	s_mov_b32 s22, 0xffe00000
	s_nop 0
	v_addc_co_u32_e32 v15, vcc, -1, v5, vcc
	v_add_co_u32_e32 v34, vcc, s22, v4
	v_pk_add_f32 v[12:13], v[12:13], v[52:53]
	s_nop 0
	v_addc_co_u32_e32 v35, vcc, -1, v5, vcc
	v_pk_add_f32 v[16:17], v[16:17], v[56:57]
	v_pk_add_f32 v[18:19], v[18:19], v[62:63]
	v_pk_add_f32 v[20:21], v[20:21], v[60:61]
	v_pk_add_f32 v[22:23], v[22:23], v[66:67]
	v_pk_add_f32 v[24:25], v[24:25], v[64:65]
	v_pk_add_f32 v[26:27], v[26:27], v[70:71]
	v_pk_add_f32 v[28:29], v[28:29], v[68:69]
	v_pk_add_f32 v[30:31], v[30:31], v[74:75]
	v_pk_add_f32 v[32:33], v[32:33], v[72:73]
	v_add_co_u32_e32 v52, vcc, s31, v4
	v_pk_add_f32 v[76:77], v[36:37], v[76:77]
	v_pk_add_f32 v[84:85], v[8:9], v[84:85]
	v_pk_add_f32 v[88:89], v[12:13], v[88:89]
	v_pk_add_f32 v[92:93], v[16:17], v[92:93]
	s_waitcnt vmcnt(3)
	v_pk_add_f32 v[94:95], v[18:19], v[98:99]
	v_pk_add_f32 v[96:97], v[20:21], v[96:97]
	s_waitcnt vmcnt(2)
	v_pk_add_f32 v[98:99], v[22:23], v[102:103]
	v_pk_add_f32 v[100:101], v[24:25], v[100:101]
	s_waitcnt vmcnt(1)
	v_pk_add_f32 v[102:103], v[26:27], v[106:107]
	v_pk_add_f32 v[104:105], v[28:29], v[104:105]
	s_waitcnt vmcnt(0)
	v_pk_add_f32 v[106:107], v[30:31], v[110:111]
	v_pk_add_f32 v[108:109], v[32:33], v[108:109]
	global_load_dwordx4 v[6:9], v[14:15], off offset:-3072
	global_load_dwordx4 v[10:13], v[14:15], off offset:-2048
	s_nop 0
	global_load_dwordx4 v[14:17], v[14:15], off offset:-1024
	s_nop 0
	global_load_dwordx4 v[18:21], v[34:35], off offset:-4096
	global_load_dwordx4 v[22:25], v[34:35], off offset:-3072
	global_load_dwordx4 v[26:29], v[34:35], off offset:-2048
	global_load_dwordx4 v[30:33], v[34:35], off offset:-1024
	s_nop 0
	global_load_dwordx4 v[34:37], v[34:35], off
	v_addc_co_u32_e32 v53, vcc, -1, v5, vcc
	global_load_dwordx4 v[44:47], v[52:53], off offset:-3072
	global_load_dwordx4 v[48:51], v[52:53], off offset:-2048
	s_nop 0
	global_load_dwordx4 v[52:55], v[52:53], off offset:-1024
	s_nop 0
	global_load_dwordx4 v[56:59], v[4:5], off offset:-4096
	global_load_dwordx4 v[60:63], v[4:5], off offset:-3072
	global_load_dwordx4 v[64:67], v[4:5], off offset:-2048
	global_load_dwordx4 v[68:71], v[4:5], off offset:-1024
	global_load_dwordx4 v[72:75], v[4:5], off
	s_waitcnt vmcnt(15)
	v_pk_add_f32 v[4:5], v[78:79], v[8:9]
	s_waitcnt vmcnt(14)
	v_pk_add_f32 v[10:11], v[84:85], v[10:11]
	v_pk_add_f32 v[6:7], v[76:77], v[6:7]
	v_pk_add_f32 v[8:9], v[80:81], v[12:13]
	s_waitcnt vmcnt(13)
	v_pk_add_f32 v[12:13], v[86:87], v[16:17]
	s_waitcnt vmcnt(8)
	v_pk_add_f32 v[36:37], v[106:107], v[36:37]
	s_waitcnt vmcnt(6)
	v_pk_add_f32 v[16:17], v[10:11], v[48:49]
	v_lshl_add_u64 v[10:11], s[20:21], 0, v[42:43]
	s_mov_b64 s[20:21], 0x21b1e000
	v_pk_add_f32 v[76:77], v[88:89], v[14:15]
	v_pk_add_f32 v[80:81], v[92:93], v[18:19]
	v_pk_add_f32 v[86:87], v[96:97], v[22:23]
	v_pk_add_f32 v[96:97], v[6:7], v[44:45]
	v_pk_add_f32 v[14:15], v[8:9], v[50:51]
	s_waitcnt vmcnt(0)
	v_pk_add_f32 v[44:45], v[36:37], v[74:75]
	v_lshl_add_u64 v[36:37], v[10:11], 0, s[20:21]
	v_add_co_u32_e32 v50, vcc, s70, v10
	s_mov_b64 s[20:21], 0xa000
	v_pk_add_f32 v[84:85], v[94:95], v[24:25]
	v_pk_add_f32 v[24:25], v[80:81], v[56:57]
	v_addc_co_u32_e32 v51, vcc, 0, v11, vcc
	v_lshl_add_u64 v[56:57], v[2:3], 0, s[20:21]
	s_mov_b32 s20, 0xb000
	v_add_co_u32_e32 v48, vcc, s20, v2
	v_pk_add_f32 v[32:33], v[102:103], v[32:33]
	v_pk_add_f32 v[34:35], v[108:109], v[34:35]
	v_addc_co_u32_e32 v49, vcc, 0, v3, vcc
	v_pk_add_f32 v[94:95], v[4:5], v[46:47]
	v_pk_add_f32 v[18:19], v[12:13], v[54:55]
	v_pk_add_f32 v[4:5], v[32:33], v[70:71]
	v_pk_add_f32 v[46:47], v[34:35], v[72:73]
	global_load_dwordx4 v[180:183], v[50:51], off offset:-4096
	global_load_dwordx4 v[184:187], v[48:49], off offset:-4096
	global_load_dwordx4 v[188:191], v[36:37], off offset:1024
	global_load_dwordx4 v[192:195], v[56:57], off offset:1024
	global_load_dwordx4 v[196:199], v[36:37], off offset:2048
	global_load_dwordx4 v[200:203], v[56:57], off offset:2048
	global_load_dwordx4 v[204:207], v[36:37], off offset:3072
	global_load_dwordx4 v[208:211], v[56:57], off offset:3072
	global_load_dwordx4 v[212:215], v[50:51], off
	global_load_dwordx4 v[216:219], v[48:49], off
	global_load_dwordx4 v[220:223], v[50:51], off offset:1024
	s_waitcnt vmcnt(0)
	s_nop 1
	v_mov_b64_e32 v[32:33], v[180:181]
	v_mov_b64_e32 v[34:35], v[182:183]
	s_nop 1
	v_mov_b64_e32 v[10:11], v[184:185]
	v_mov_b64_e32 v[12:13], v[186:187]
	v_pk_add_f32 v[78:79], v[90:91], v[20:21]
	v_pk_add_f32 v[20:21], v[76:77], v[52:53]
	v_pk_add_f32 v[22:23], v[78:79], v[58:59]
	v_pk_add_f32 v[88:89], v[98:99], v[28:29]
	v_pk_add_f32 v[90:91], v[100:101], v[26:27]
	v_pk_add_f32 v[26:27], v[84:85], v[62:63]
	v_pk_add_f32 v[28:29], v[86:87], v[60:61]
	v_pk_add_f32 v[8:9], v[88:89], v[66:67]
	v_pk_add_f32 v[92:93], v[104:105], v[30:31]
	v_pk_add_f32 v[30:31], v[90:91], v[64:65]
	v_pk_add_f32 v[6:7], v[92:93], v[68:69]
	s_nop 0
	v_pk_add_f32 v[2:3], v[12:13], 1.0 op_sel_hi:[1,0]
	v_pk_add_f32 v[10:11], v[10:11], 1.0 op_sel_hi:[1,0]
	v_pk_mul_f32 v[2:3], v[94:95], v[2:3]
	v_pk_mul_f32 v[12:13], v[96:97], v[10:11]
	v_pk_fma_f32 v[10:11], v[34:35], s[92:93], v[2:3] op_sel_hi:[1,0,1]
	v_pk_fma_f32 v[12:13], v[32:33], s[92:93], v[12:13] op_sel_hi:[1,0,1]
	s_nop 1
	v_mov_b64_e32 v[32:33], v[188:189]
	v_mov_b64_e32 v[34:35], v[190:191]
	s_nop 1
	v_mov_b64_e32 v[52:53], v[192:193]
	v_mov_b64_e32 v[54:55], v[194:195]
	s_nop 0
	v_pk_add_f32 v[2:3], v[54:55], 1.0 op_sel_hi:[1,0]
	v_pk_add_f32 v[52:53], v[52:53], 1.0 op_sel_hi:[1,0]
	v_pk_mul_f32 v[2:3], v[14:15], v[2:3]
	v_pk_mul_f32 v[16:17], v[16:17], v[52:53]
	v_pk_fma_f32 v[14:15], v[34:35], s[92:93], v[2:3] op_sel_hi:[1,0,1]
	v_pk_fma_f32 v[16:17], v[32:33], s[92:93], v[16:17] op_sel_hi:[1,0,1]
	s_nop 1
	v_mov_b64_e32 v[32:33], v[196:197]
	v_mov_b64_e32 v[34:35], v[198:199]
	s_nop 1
	v_mov_b64_e32 v[52:53], v[200:201]
	v_mov_b64_e32 v[54:55], v[202:203]
	s_nop 0
	v_pk_add_f32 v[2:3], v[54:55], 1.0 op_sel_hi:[1,0]
	v_pk_add_f32 v[52:53], v[52:53], 1.0 op_sel_hi:[1,0]
	v_pk_mul_f32 v[2:3], v[18:19], v[2:3]
	v_pk_mul_f32 v[20:21], v[20:21], v[52:53]
	v_pk_fma_f32 v[18:19], v[34:35], s[92:93], v[2:3] op_sel_hi:[1,0,1]
	v_pk_fma_f32 v[20:21], v[32:33], s[92:93], v[20:21] op_sel_hi:[1,0,1]
	s_nop 1
	v_mov_b64_e32 v[32:33], v[204:205]
	v_mov_b64_e32 v[34:35], v[206:207]
	s_nop 1
	v_mov_b64_e32 v[52:53], v[208:209]
	v_mov_b64_e32 v[54:55], v[210:211]
	s_nop 0
	v_pk_add_f32 v[2:3], v[54:55], 1.0 op_sel_hi:[1,0]
	v_pk_add_f32 v[36:37], v[52:53], 1.0 op_sel_hi:[1,0]
	v_pk_mul_f32 v[2:3], v[22:23], v[2:3]
	v_pk_mul_f32 v[24:25], v[24:25], v[36:37]
	v_pk_fma_f32 v[22:23], v[34:35], s[92:93], v[2:3] op_sel_hi:[1,0,1]
	v_pk_fma_f32 v[24:25], v[32:33], s[92:93], v[24:25] op_sel_hi:[1,0,1]
	s_nop 1
	v_mov_b64_e32 v[32:33], v[212:213]
	v_mov_b64_e32 v[34:35], v[214:215]
	s_nop 1
	v_mov_b64_e32 v[52:53], v[216:217]
	v_mov_b64_e32 v[54:55], v[218:219]
	s_nop 0
	v_pk_add_f32 v[2:3], v[54:55], 1.0 op_sel_hi:[1,0]
	v_pk_add_f32 v[36:37], v[52:53], 1.0 op_sel_hi:[1,0]
	v_pk_mul_f32 v[2:3], v[26:27], v[2:3]
	v_pk_mul_f32 v[28:29], v[28:29], v[36:37]
	v_pk_fma_f32 v[26:27], v[34:35], s[92:93], v[2:3] op_sel_hi:[1,0,1]
	v_pk_fma_f32 v[28:29], v[32:33], s[92:93], v[28:29] op_sel_hi:[1,0,1]
	s_nop 1
	v_mov_b64_e32 v[32:33], v[220:221]
	v_mov_b64_e32 v[34:35], v[222:223]
	global_load_dwordx4 v[180:183], v[48:49], off offset:1024
	global_load_dwordx4 v[184:187], v[50:51], off offset:2048
	global_load_dwordx4 v[188:191], v[48:49], off offset:2048
	global_load_dwordx4 v[192:195], v[50:51], off offset:3072
	global_load_dwordx4 v[196:199], v[48:49], off offset:3072
	s_waitcnt vmcnt(0)
	s_nop 1
	v_mov_b64_e32 v[52:53], v[180:181]
	v_mov_b64_e32 v[54:55], v[182:183]
	s_nop 0
	v_pk_add_f32 v[2:3], v[54:55], 1.0 op_sel_hi:[1,0]
	v_pk_add_f32 v[36:37], v[52:53], 1.0 op_sel_hi:[1,0]
	v_pk_mul_f32 v[2:3], v[8:9], v[2:3]
	v_pk_mul_f32 v[8:9], v[30:31], v[36:37]
	v_pk_fma_f32 v[30:31], v[34:35], s[92:93], v[2:3] op_sel_hi:[1,0,1]
	s_nop 1
	v_mov_b64_e32 v[52:53], v[184:185]
	v_mov_b64_e32 v[54:55], v[186:187]
	s_nop 1
	v_mov_b64_e32 v[34:35], v[188:189]
	v_mov_b64_e32 v[36:37], v[190:191]
	v_pk_fma_f32 v[32:33], v[32:33], s[92:93], v[8:9] op_sel_hi:[1,0,1]
	s_nop 0
	v_pk_add_f32 v[2:3], v[36:37], 1.0 op_sel_hi:[1,0]
	v_pk_add_f32 v[8:9], v[34:35], 1.0 op_sel_hi:[1,0]
	v_pk_mul_f32 v[2:3], v[4:5], v[2:3]
	v_pk_mul_f32 v[4:5], v[6:7], v[8:9]
	v_pk_fma_f32 v[34:35], v[54:55], s[92:93], v[2:3] op_sel_hi:[1,0,1]
	v_pk_fma_f32 v[36:37], v[52:53], s[92:93], v[4:5] op_sel_hi:[1,0,1]
	s_nop 1
	v_mov_b64_e32 v[2:3], v[192:193]
	v_mov_b64_e32 v[4:5], v[194:195]
	s_nop 1
	v_mov_b64_e32 v[6:7], v[196:197]
	v_mov_b64_e32 v[8:9], v[198:199]
	v_add_f32_e32 v48, v22, v23
	v_mov_b32_e32 v49, v27
	s_load_dwordx4 s[36:39], s[8:9], 0xb0
	s_waitcnt lgkmcnt(0)
	s_add_u32 s22, s36, s40
	s_addc_u32 s23, s37, s41
	s_add_u32 s24, s38, s40
	s_addc_u32 s25, s39, s41
	s_add_u32 s18, s30, s18
	s_addc_u32 s19, s27, s19
	s_and_b64 s[20:21], s[34:35], exec
	s_cselect_b32 s17, s17, 0
	s_cselect_b32 s16, s16, 0
	s_lshl_b64 s[16:17], s[16:17], 1
	s_add_u32 s20, s29, s16
	s_addc_u32 s21, s26, s17
	s_load_dwordx2 s[16:17], s[8:9], 0x68
	s_nop 0
	v_pk_add_f32 v[8:9], v[8:9], 1.0 op_sel_hi:[1,0]
	v_pk_add_f32 v[6:7], v[6:7], 1.0 op_sel_hi:[1,0]
	v_pk_mul_f32 v[8:9], v[44:45], v[8:9]
	v_pk_mul_f32 v[6:7], v[46:47], v[6:7]
	v_pk_fma_f32 v[44:45], v[4:5], s[92:93], v[8:9] op_sel_hi:[1,0,1]
	v_pk_fma_f32 v[8:9], v[2:3], s[92:93], v[6:7] op_sel_hi:[1,0,1]
	v_mov_b32_e32 v2, v12
	v_mov_b32_e32 v3, v16
	v_mov_b32_e32 v4, v13
	v_mov_b32_e32 v5, v17
	v_pk_add_f32 v[2:3], v[2:3], v[4:5]
	v_mov_b32_e32 v4, v10
	v_mov_b32_e32 v5, v14
	v_mov_b32_e32 v46, v11
	v_mov_b32_e32 v47, v15
	v_pk_add_f32 v[4:5], v[4:5], v[46:47]
	v_mov_b32_e32 v46, v20
	v_pk_add_f32 v[2:3], v[2:3], v[4:5]
	v_pk_mov_b32 v[4:5], v[20:21], v[18:19] op_sel:[1,0]
	v_mov_b32_e32 v47, v19
	v_pk_add_f32 v[4:5], v[4:5], v[46:47]
	v_add_f32_e32 v2, 0, v2
	v_pk_add_f32 v[4:5], v[4:5], v[4:5] op_sel:[0,1] op_sel_hi:[1,0]
	v_add_f32_e32 v2, v2, v3
	v_add_f32_e32 v46, v24, v25
	v_mov_b32_e32 v3, v28
	v_mov_b32_e32 v5, v29
	v_mov_b32_e32 v47, v26
	v_pk_add_f32 v[2:3], v[2:3], v[4:5]
	v_pk_add_f32 v[4:5], v[46:47], v[48:49]
	v_mov_b32_e32 v46, v32
	v_pk_add_f32 v[2:3], v[2:3], v[4:5]
	v_pk_mov_b32 v[4:5], v[32:33], v[30:31] op_sel:[1,0]
	v_mov_b32_e32 v47, v31
	v_pk_add_f32 v[4:5], v[4:5], v[46:47]
	v_pk_add_f32 v[2:3], v[2:3], v[2:3] op_sel:[0,1] op_sel_hi:[1,0]
	v_pk_add_f32 v[4:5], v[4:5], v[4:5] op_sel:[0,1] op_sel_hi:[1,0]
	v_add_f32_e32 v46, v36, v37
	v_add_f32_e32 v48, v34, v35
	v_mov_b32_e32 v3, v8
	v_mov_b32_e32 v5, v9
	v_mov_b32_e32 v47, v44
	v_mov_b32_e32 v49, v45
	v_pk_add_f32 v[2:3], v[2:3], v[4:5]
	v_pk_add_f32 v[4:5], v[46:47], v[48:49]
	v_lshl_add_u64 v[6:7], v[38:39], 0, s[6:7]
	v_pk_add_f32 v[2:3], v[2:3], v[4:5]
	v_xor_b32_e32 v4, 1, v249
	v_add_f32_e32 v2, v2, v3
	v_and_b32_e32 v3, 64, v249
	v_add_u32_e32 v3, 64, v3
	v_cmp_lt_i32_e32 vcc, v4, v3
	s_nop 1
	v_cndmask_b32_e32 v4, v249, v4, vcc
	v_lshlrev_b32_e32 v58, 2, v4
	ds_bpermute_b32 v4, v58, v2
	s_waitcnt lgkmcnt(0)
	v_add_f32_e32 v2, v2, v4
	v_xor_b32_e32 v4, 2, v249
	v_cmp_lt_i32_e32 vcc, v4, v3
	s_nop 1
	v_cndmask_b32_e32 v4, v249, v4, vcc
	v_lshlrev_b32_e32 v59, 2, v4
	ds_bpermute_b32 v4, v59, v2
	s_waitcnt lgkmcnt(0)
	v_add_f32_e32 v2, v2, v4
	v_xor_b32_e32 v4, 4, v249
	v_cmp_lt_i32_e32 vcc, v4, v3
	s_nop 1
	v_cndmask_b32_e32 v4, v249, v4, vcc
	v_lshlrev_b32_e32 v60, 2, v4
	ds_bpermute_b32 v4, v60, v2
	s_waitcnt lgkmcnt(0)
	v_add_f32_e32 v2, v2, v4
	v_xor_b32_e32 v4, 8, v249
	v_cmp_lt_i32_e32 vcc, v4, v3
	s_nop 1
	v_cndmask_b32_e32 v4, v249, v4, vcc
	v_lshlrev_b32_e32 v61, 2, v4
	ds_bpermute_b32 v4, v61, v2
	s_waitcnt lgkmcnt(0)
	v_add_f32_e32 v2, v2, v4
	v_xor_b32_e32 v4, 16, v249
	v_cmp_lt_i32_e32 vcc, v4, v3
	s_nop 1
	v_cndmask_b32_e32 v4, v249, v4, vcc
	v_lshlrev_b32_e32 v62, 2, v4
	ds_bpermute_b32 v4, v62, v2
	s_waitcnt lgkmcnt(0)
	v_add_f32_e32 v2, v2, v4
	v_xor_b32_e32 v4, 32, v249
	v_cmp_lt_i32_e32 vcc, v4, v3
	s_nop 1
	v_cndmask_b32_e32 v3, v249, v4, vcc
	v_lshlrev_b32_e32 v63, 2, v3
	ds_bpermute_b32 v3, v63, v2
	s_waitcnt lgkmcnt(0)
	v_add_f32_e32 v50, v2, v3
	v_fmamk_f32 v13, v50, 0xba000000, v13
	v_fmamk_f32 v17, v50, 0xba000000, v17
	v_fmamk_f32 v11, v50, 0xba000000, v11
	v_fmac_f32_e32 v12, 0xba000000, v50
	v_fmamk_f32 v15, v50, 0xba000000, v15
	v_fmac_f32_e32 v16, 0xba000000, v50
	v_mov_b32_e32 v4, v13
	v_mov_b32_e32 v5, v17
	v_fmac_f32_e32 v10, 0xba000000, v50
	v_fmac_f32_e32 v14, 0xba000000, v50
	v_mov_b32_e32 v2, v12
	v_mov_b32_e32 v3, v16
	v_pk_mul_f32 v[4:5], v[4:5], v[4:5]
	v_mov_b32_e32 v46, v11
	v_mov_b32_e32 v47, v15
	v_pk_fma_f32 v[2:3], v[2:3], v[2:3], v[4:5]
	v_mov_b32_e32 v4, v10
	v_mov_b32_e32 v5, v14
	v_pk_mul_f32 v[46:47], v[46:47], v[46:47]
	v_fmamk_f32 v21, v50, 0xba000000, v21
	v_pk_fma_f32 v[4:5], v[4:5], v[4:5], v[46:47]
	v_fmac_f32_e32 v20, 0xba000000, v50
	v_pk_add_f32 v[2:3], v[2:3], v[4:5]
	v_fmamk_f32 v19, v50, 0xba000000, v19
	v_fmac_f32_e32 v18, 0xba000000, v50
	v_pk_add_f32 v[2:3], v[2:3], v[2:3] op_sel_hi:[0,1]
	v_pk_mul_f32 v[4:5], v[18:19], v[18:19]
	v_pk_mul_f32 v[46:47], v[20:21], v[20:21]
	v_fmac_f32_e32 v24, 0xba000000, v50
	v_pk_mov_b32 v[48:49], v[46:47], v[4:5] op_sel:[1,0]
	v_mov_b32_e32 v47, v5
	v_fmamk_f32 v25, v50, 0xba000000, v25
	v_fmac_f32_e32 v22, 0xba000000, v50
	v_mul_f32_e32 v2, v24, v24
	v_pk_add_f32 v[4:5], v[48:49], v[46:47]
	v_fmamk_f32 v23, v50, 0xba000000, v23
	v_pk_fma_f32 v[46:47], v[24:25], v[24:25], v[2:3] op_sel_hi:[1,1,0]
	v_mul_f32_e32 v2, v22, v22
	v_pk_add_f32 v[4:5], v[4:5], v[4:5] op_sel_hi:[0,1]
	v_pk_fma_f32 v[48:49], v[22:23], v[22:23], v[2:3] op_sel_hi:[1,1,0]
	v_fmamk_f32 v27, v50, 0xba000000, v27
	v_fmac_f32_e32 v26, 0xba000000, v50
	v_fmamk_f32 v29, v50, 0xba000000, v29
	v_fmac_f32_e32 v28, 0xba000000, v50
	v_mul_f32_e32 v46, v28, v28
	v_mul_f32_e32 v48, v29, v29
	v_mul_f32_e32 v4, v26, v26
	v_mul_f32_e32 v2, v27, v27
	v_pk_add_f32 v[46:47], v[46:47], v[48:49]
	v_pk_add_f32 v[2:3], v[4:5], v[2:3]
	v_fmamk_f32 v33, v50, 0xba000000, v33
	v_pk_add_f32 v[2:3], v[46:47], v[2:3]
	v_fmac_f32_e32 v32, 0xba000000, v50
	v_fmamk_f32 v31, v50, 0xba000000, v31
	v_fmac_f32_e32 v30, 0xba000000, v50
	v_pk_add_f32 v[2:3], v[2:3], v[2:3] op_sel_hi:[0,1]
	v_pk_mul_f32 v[4:5], v[30:31], v[30:31]
	v_pk_mul_f32 v[46:47], v[32:33], v[32:33]
	v_fmac_f32_e32 v36, 0xba000000, v50
	v_pk_mov_b32 v[48:49], v[46:47], v[4:5] op_sel:[1,0]
	v_mov_b32_e32 v47, v5
	v_fmamk_f32 v37, v50, 0xba000000, v37
	v_fmac_f32_e32 v34, 0xba000000, v50
	v_mul_f32_e32 v2, v36, v36
	v_pk_add_f32 v[4:5], v[48:49], v[46:47]
	v_fmamk_f32 v35, v50, 0xba000000, v35
	v_pk_fma_f32 v[46:47], v[36:37], v[36:37], v[2:3] op_sel_hi:[1,1,0]
	v_mul_f32_e32 v2, v34, v34
	v_pk_add_f32 v[4:5], v[4:5], v[4:5] op_sel_hi:[0,1]
	v_pk_fma_f32 v[48:49], v[34:35], v[34:35], v[2:3] op_sel_hi:[1,1,0]
	v_fmamk_f32 v45, v50, 0xba000000, v45
	v_fmac_f32_e32 v44, 0xba000000, v50
	v_fmamk_f32 v9, v50, 0xba000000, v9
	v_fmac_f32_e32 v8, 0xba000000, v50
	v_mul_f32_e32 v46, v8, v8
	v_mul_f32_e32 v48, v9, v9
	v_mul_f32_e32 v4, v44, v44
	v_mul_f32_e32 v2, v45, v45
	v_pk_add_f32 v[46:47], v[46:47], v[48:49]
	v_pk_add_f32 v[2:3], v[4:5], v[2:3]
	v_lshl_add_u64 v[50:51], s[22:23], 0, v[42:43]
	v_pk_add_f32 v[2:3], v[46:47], v[2:3]
	v_lshl_add_u64 v[48:49], s[24:25], 0, v[42:43]
	v_add_f32_e32 v2, v2, v3
	ds_bpermute_b32 v3, v58, v2
	global_load_dwordx4 v[52:55], v[48:49], off
	s_waitcnt lgkmcnt(0)
	v_add_f32_e32 v2, v2, v3
	ds_bpermute_b32 v3, v59, v2
	s_waitcnt lgkmcnt(0)
	v_add_f32_e32 v2, v2, v3
	ds_bpermute_b32 v3, v60, v2
	s_waitcnt lgkmcnt(0)
	v_add_f32_e32 v2, v2, v3
	ds_bpermute_b32 v3, v61, v2
	s_waitcnt lgkmcnt(0)
	v_add_f32_e32 v2, v2, v3
	ds_bpermute_b32 v3, v62, v2
	s_waitcnt lgkmcnt(0)
	v_add_f32_e32 v2, v2, v3
	ds_bpermute_b32 v3, v63, v2
	s_waitcnt lgkmcnt(0)
	v_add_f32_e32 v2, v2, v3
	v_fmamk_f32 v2, v2, 0x3a000000, v250
	v_cmp_gt_f32_e32 vcc, s96, v2
	v_mul_f32_e32 v3, 0x4f800000, v2
	s_nop 0
	v_cndmask_b32_e32 v2, v2, v3, vcc
	v_sqrt_f32_e32 v3, v2
	s_nop 0
	v_add_u32_e32 v4, -1, v3
	v_fma_f32 v5, -v4, v3, v2
	v_cmp_ge_f32_e64 s[8:9], 0, v5
	v_add_u32_e32 v5, 1, v3
	s_nop 0
	v_cndmask_b32_e64 v4, v3, v4, s[8:9]
	v_fma_f32 v3, -v5, v3, v2
	v_cmp_lt_f32_e64 s[8:9], 0, v3
	s_nop 1
	v_cndmask_b32_e64 v3, v4, v5, s[8:9]
	v_mul_f32_e32 v4, 0x37800000, v3
	v_cndmask_b32_e32 v3, v3, v4, vcc
	v_cmp_class_f32_e32 vcc, v2, v251
	s_nop 1
	v_cndmask_b32_e32 v2, v3, v2, vcc
	v_div_scale_f32 v3, s[8:9], v2, v2, 1.0
	v_rcp_f32_e32 v4, v3
	s_nop 0
	v_fma_f32 v5, -v3, v4, 1.0
	v_fmac_f32_e32 v4, v5, v4
	v_div_scale_f32 v5, vcc, 1.0, v2, 1.0
	v_mul_f32_e32 v46, v5, v4
	v_fma_f32 v47, -v3, v46, v5
	v_fmac_f32_e32 v46, v47, v4
	v_fma_f32 v3, -v3, v46, v5
	v_div_fmas_f32 v3, v3, v4, v46
	v_div_fixup_f32 v46, v3, v2, 1.0
	global_load_dwordx4 v[2:5], v[50:51], off
	v_pk_mul_f32 v[56:57], v[12:13], v[46:47] op_sel_hi:[1,0]
	v_pk_mul_f32 v[64:65], v[10:11], v[46:47] op_sel_hi:[1,0]
	v_cndmask_b32_e64 v47, 0, 1, s[34:35]
	v_cmp_ne_u32_e64 s[8:9], 1, v47
	s_andn2_b64 vcc, exec, s[34:35]
	s_waitcnt vmcnt(0)
	v_pk_fma_f32 v[4:5], v[4:5], v[64:65], v[54:55]
	v_pk_fma_f32 v[2:3], v[2:3], v[56:57], v[52:53]
	v_lshl_add_u64 v[54:55], s[18:19], 0, v[42:43]
	v_lshl_add_u64 v[52:53], v[40:41], 1, s[20:21]
	global_store_dwordx4 v[54:55], v[2:5], off
	s_cbranch_vccnz .LBB0_1760
	v_lshl_add_u64 v[10:11], v[6:7], 0, v[42:43]
	global_load_dwordx4 v[10:13], v[10:11], off
	v_lshl_add_u64 v[42:43], v[38:39], 0, v[42:43]
	global_load_dwordx4 v[64:67], v[42:43], off
	s_waitcnt vmcnt(1)
	v_pk_add_f32 v[12:13], v[12:13], 1.0 op_sel_hi:[1,0]
	v_pk_add_f32 v[42:43], v[10:11], 1.0 op_sel_hi:[1,0]
	s_waitcnt vmcnt(0)
	v_pk_fma_f32 v[10:11], v[4:5], v[12:13], v[66:67]
	v_pk_fma_f32 v[12:13], v[2:3], v[42:43], v[64:65]
	v_bfe_u32 v4, v10, 16, 1
	v_bfe_u32 v5, v11, 16, 1
	v_add3_u32 v4, v10, v4, s73
	v_add3_u32 v5, v11, v5, s73
	v_lshrrev_b32_e32 v4, 16, v4
	v_cvt_pk_bf16_f32 v2, v12, v13
	v_and_or_b32 v3, v5, s33, v4
	global_store_dwordx2 v[52:53], v[2:3], off
